# SwiGLU epilogue: the 8 per-row ssq loads issued together with one wait instead of 8 serialized round trips
# speedup vs baseline: 1.0149x; 1.0117x over previous
.LBB0_161:
	s_lshl_b32 s5, s12, 8
	v_mov_b32_e32 v82, v159
	v_mov_b32_e32 v83, v1
	s_add_i32 s5, s5, s31
	s_nop 0
	v_add_u32_e32 v182, s5, v82
	s_lshl_b32 s5, s42, 7
	s_or_b32 s5, s5, s34
	v_lshl_add_u32 v186, v83, 3, s5
	s_ashr_i32 s5, s12, 5
	s_mul_hi_i32 s7, s5, 0x5800
	s_mulk_i32 s5, 0x5800
	s_add_u32 s14, s28, s5
	s_addc_u32 s15, s29, s7
	v_ashrrev_i32_e32 v187, 31, v186
	v_lshl_add_u64 v[86:87], v[186:187], 2, s[14:15]
	s_mov_b64 s[14:15], 0x2c00
	s_movk_i32 s5, 0x2000
	global_load_dwordx4 v[82:85], v[86:87], off offset:16
	global_load_dwordx4 v[98:101], v[86:87], off
	v_lshl_add_u64 v[88:89], v[86:87], 0, s[14:15]
	v_add_co_u32_e32 v86, vcc, s5, v86
	v_ashrrev_i32_e32 v183, 31, v182
	s_nop 0
	v_addc_co_u32_e32 v87, vcc, 0, v87, vcc
	v_lshl_add_u64 v[160:161], v[182:183], 2, s[0:1]
	global_load_dwordx4 v[102:105], v[86:87], off offset:3072
	s_nop 0
	global_load_dwordx4 v[86:89], v[88:89], off offset:16
	v_add_u32_e32 v187, 16, v182
	global_load_dword v184, v[160:161], off
	global_load_dword v180, v[160:161], off offset:64
	global_load_dword v178, v[160:161], off offset:128
	global_load_dword v176, v[160:161], off offset:192
	global_load_dword v174, v[160:161], off offset:512
	global_load_dword v172, v[160:161], off offset:576
	global_load_dword v175, v[160:161], off offset:640
	global_load_dword v160, v[160:161], off offset:704
	v_add_u32_e32 v185, 32, v182
	v_add_u32_e32 v183, 48, v182
	v_add_u32_e32 v181, 0x80, v182
	v_add_u32_e32 v179, 0x90, v182
	v_add_u32_e32 v177, 0xa0, v182
	s_waitcnt vmcnt(0)
	v_fmamk_f32 v158, v184, 0x3a800000, v223
	v_cmp_gt_f32_e32 vcc, s95, v158
	v_mul_f32_e32 v168, 0x4b800000, v158
	s_nop 0
	v_cndmask_b32_e32 v158, v158, v168, vcc
	v_rsq_f32_e32 v158, v158
	s_nop 0
	v_mul_f32_e32 v168, 0x45800000, v158
	v_cndmask_b32_e32 v184, v158, v168, vcc
	v_fmamk_f32 v158, v180, 0x3a800000, v223
	v_cmp_gt_f32_e32 vcc, s95, v158
	v_mul_f32_e32 v168, 0x4b800000, v158
	s_nop 0
	v_cndmask_b32_e32 v158, v158, v168, vcc
	v_rsq_f32_e32 v158, v158
	s_nop 0
	v_mul_f32_e32 v168, 0x45800000, v158
	v_cndmask_b32_e32 v180, v158, v168, vcc
	v_fmamk_f32 v158, v178, 0x3a800000, v223
	v_cmp_gt_f32_e32 vcc, s95, v158
	v_mul_f32_e32 v168, 0x4b800000, v158
	s_nop 0
	v_cndmask_b32_e32 v158, v158, v168, vcc
	v_rsq_f32_e32 v158, v158
	s_nop 0
	v_mul_f32_e32 v168, 0x45800000, v158
	v_cndmask_b32_e32 v178, v158, v168, vcc
	v_fmamk_f32 v158, v176, 0x3a800000, v223
	v_cmp_gt_f32_e32 vcc, s95, v158
	v_mul_f32_e32 v168, 0x4b800000, v158
	s_nop 0
	v_cndmask_b32_e32 v158, v158, v168, vcc
	v_rsq_f32_e32 v158, v158
	s_nop 0
	v_mul_f32_e32 v168, 0x45800000, v158
	v_cndmask_b32_e32 v176, v158, v168, vcc
	v_fmamk_f32 v158, v174, 0x3a800000, v223
	v_cmp_gt_f32_e32 vcc, s95, v158
	v_mul_f32_e32 v168, 0x4b800000, v158
	s_nop 0
	v_cndmask_b32_e32 v158, v158, v168, vcc
	v_rsq_f32_e32 v158, v158
	s_nop 0
	v_mul_f32_e32 v168, 0x45800000, v158
	v_cndmask_b32_e32 v174, v158, v168, vcc
	v_fmamk_f32 v158, v172, 0x3a800000, v223
	v_cmp_gt_f32_e32 vcc, s95, v158
	v_mul_f32_e32 v168, 0x4b800000, v158
	s_nop 0
	v_cndmask_b32_e32 v158, v158, v168, vcc
	v_rsq_f32_e32 v158, v158
	s_nop 0
	v_mul_f32_e32 v168, 0x45800000, v158
	v_cndmask_b32_e32 v172, v158, v168, vcc
	v_fmamk_f32 v158, v175, 0x3a800000, v223
	v_add_u32_e32 v175, 0xb0, v182
	v_cmp_gt_f32_e32 vcc, s95, v158
	v_mul_f32_e32 v168, 0x4b800000, v158
	v_fmamk_f32 v160, v160, 0x3a800000, v223
	v_cndmask_b32_e32 v158, v158, v168, vcc
	v_rsq_f32_e32 v158, v158
	v_mul_f32_e32 v161, 0x4b800000, v160
	v_mul_f32_e32 v168, 0x45800000, v158
	v_cndmask_b32_e32 v158, v158, v168, vcc
	v_cmp_gt_f32_e32 vcc, s95, v160
	s_nop 1
	v_cndmask_b32_e32 v160, v160, v161, vcc
	v_rsq_f32_e32 v160, v160
	s_nop 0
	v_mul_f32_e32 v161, 0x45800000, v160
	v_cndmask_b32_e32 v160, v160, v161, vcc
	v_ashrrev_i32_e32 v161, 6, v186
	v_and_b32_e32 v186, 56, v186
	v_pk_fma_f32 v[138:139], v[138:139], v[184:185], v[98:99] op_sel_hi:[1,0,1]
	v_pk_fma_f32 v[142:143], v[142:143], v[184:185], v[102:103] op_sel_hi:[1,0,1]
	v_mul_f32_e32 v168, 0xbfb8aa3b, v138
	v_mul_f32_e32 v169, 0xbfb8aa3b, v139
	v_exp_f32_e32 v168, v168
	v_exp_f32_e32 v169, v169
	v_pk_fma_f32 v[140:141], v[140:141], v[184:185], v[100:101] op_sel_hi:[1,0,1]
	v_pk_fma_f32 v[134:135], v[134:135], v[184:185], v[82:83] op_sel_hi:[1,0,1]
	v_add_f32_e32 v168, 1.0, v168
	v_add_f32_e32 v169, 1.0, v169
	v_rcp_f32_e32 v168, v168
	v_rcp_f32_e32 v169, v169
	v_pk_fma_f32 v[130:131], v[130:131], v[184:185], v[86:87] op_sel_hi:[1,0,1]
	v_pk_fma_f32 v[132:133], v[132:133], v[184:185], v[88:89] op_sel_hi:[1,0,1]
	v_readlane_b32 s14, v254, 27
	v_pk_mul_f32 v[138:139], v[138:139], v[168:169]
	v_readlane_b32 s15, v254, 28
	v_pk_mul_f32 v[138:139], v[142:143], v[138:139]
	v_pk_fma_f32 v[142:143], v[144:145], v[184:185], v[104:105] op_sel_hi:[1,0,1]
	v_mul_f32_e32 v144, 0xbfb8aa3b, v140
	v_mul_f32_e32 v145, 0xbfb8aa3b, v141
	v_exp_f32_e32 v144, v144
	v_exp_f32_e32 v145, v145
	v_add_f32_e32 v144, 1.0, v144
	v_add_f32_e32 v145, 1.0, v145
	v_rcp_f32_e32 v144, v144
	v_rcp_f32_e32 v145, v145
	s_nop 0
	v_pk_mul_f32 v[140:141], v[140:141], v[144:145]
	s_nop 0
	v_pk_mul_f32 v[140:141], v[142:143], v[140:141]
	v_mul_f32_e32 v142, 0xbfb8aa3b, v134
	v_mul_f32_e32 v143, 0xbfb8aa3b, v135
	v_exp_f32_e32 v142, v142
	v_exp_f32_e32 v143, v143
	v_add_f32_e32 v142, 1.0, v142
	v_add_f32_e32 v143, 1.0, v143
	v_rcp_f32_e32 v142, v142
	v_rcp_f32_e32 v143, v143
	s_nop 0
	v_pk_mul_f32 v[134:135], v[134:135], v[142:143]
	s_nop 0
	v_pk_mul_f32 v[130:131], v[130:131], v[134:135]
	v_pk_fma_f32 v[134:135], v[136:137], v[184:185], v[84:85] op_sel_hi:[1,0,1]
	s_nop 0
	v_mul_f32_e32 v136, 0xbfb8aa3b, v134
	v_mul_f32_e32 v137, 0xbfb8aa3b, v135
	v_exp_f32_e32 v136, v136
	v_exp_f32_e32 v137, v137
	v_add_f32_e32 v136, 1.0, v136
	v_add_f32_e32 v137, 1.0, v137
	v_rcp_f32_e32 v136, v136
	v_rcp_f32_e32 v137, v137
	s_nop 0
	v_pk_mul_f32 v[134:135], v[134:135], v[136:137]
	s_nop 0
	v_pk_mul_f32 v[136:137], v[132:133], v[134:135]
	v_cvt_pk_bf16_f32 v134, v130, v131
	v_lshrrev_b32_e32 v130, 8, v182
	v_mad_i32_i24 v130, v130, 44, v161
	v_ashrrev_i32_e32 v131, 31, v130
	v_cvt_pk_bf16_f32 v135, v136, v137
	v_lshlrev_b64 v[130:131], 15, v[130:131]
	v_lshlrev_b32_e32 v136, 7, v182
	v_lshl_add_u64 v[130:131], s[14:15], 0, v[130:131]
	v_and_b32_e32 v136, 0x7f80, v136
	v_mov_b32_e32 v137, v0
	v_lshl_add_u64 v[136:137], v[130:131], 0, v[136:137]
	v_lshlrev_b32_e32 v130, 1, v186
	v_mov_b32_e32 v131, v0
	v_cvt_pk_bf16_f32 v132, v138, v139
	v_cvt_pk_bf16_f32 v133, v140, v141
	v_lshl_add_u64 v[136:137], v[136:137], 0, v[130:131]
	global_store_dwordx4 v[136:137], v[132:135], off nt
	v_pk_fma_f32 v[126:127], v[126:127], v[180:181], v[98:99] op_sel_hi:[1,0,1]
	v_pk_fma_f32 v[122:123], v[122:123], v[180:181], v[102:103] op_sel_hi:[1,0,1]
	v_mul_f32_e32 v132, 0xbfb8aa3b, v126
	v_mul_f32_e32 v133, 0xbfb8aa3b, v127
	v_exp_f32_e32 v132, v132
	v_exp_f32_e32 v133, v133
	v_pk_fma_f32 v[124:125], v[124:125], v[180:181], v[104:105] op_sel_hi:[1,0,1]
	v_pk_fma_f32 v[118:119], v[118:119], v[180:181], v[82:83] op_sel_hi:[1,0,1]
	v_add_f32_e32 v132, 1.0, v132
	v_add_f32_e32 v133, 1.0, v133
	v_rcp_f32_e32 v132, v132
	v_rcp_f32_e32 v133, v133
	v_pk_fma_f32 v[114:115], v[114:115], v[180:181], v[86:87] op_sel_hi:[1,0,1]
	v_pk_fma_f32 v[116:117], v[116:117], v[180:181], v[88:89] op_sel_hi:[1,0,1]
	v_pk_mul_f32 v[126:127], v[126:127], v[132:133]
	s_nop 0
	v_pk_mul_f32 v[122:123], v[122:123], v[126:127]
	v_pk_fma_f32 v[126:127], v[128:129], v[180:181], v[100:101] op_sel_hi:[1,0,1]
	s_nop 0
	v_mul_f32_e32 v128, 0xbfb8aa3b, v126
	v_mul_f32_e32 v129, 0xbfb8aa3b, v127
	v_exp_f32_e32 v128, v128
	v_exp_f32_e32 v129, v129
	v_add_f32_e32 v128, 1.0, v128
	v_add_f32_e32 v129, 1.0, v129
	v_rcp_f32_e32 v128, v128
	v_rcp_f32_e32 v129, v129
	s_nop 0
	v_pk_mul_f32 v[126:127], v[126:127], v[128:129]
	s_nop 0
	v_pk_mul_f32 v[124:125], v[124:125], v[126:127]
	v_mul_f32_e32 v126, 0xbfb8aa3b, v118
	v_mul_f32_e32 v127, 0xbfb8aa3b, v119
	v_exp_f32_e32 v126, v126
	v_exp_f32_e32 v127, v127
	v_add_f32_e32 v126, 1.0, v126
	v_add_f32_e32 v127, 1.0, v127
	v_rcp_f32_e32 v126, v126
	v_rcp_f32_e32 v127, v127
	s_nop 0
	v_pk_mul_f32 v[118:119], v[118:119], v[126:127]
	s_nop 0
	v_pk_mul_f32 v[118:119], v[114:115], v[118:119]
	v_pk_fma_f32 v[114:115], v[120:121], v[180:181], v[84:85] op_sel_hi:[1,0,1]
	s_nop 0
	v_mul_f32_e32 v120, 0xbfb8aa3b, v114
	v_mul_f32_e32 v121, 0xbfb8aa3b, v115
	v_exp_f32_e32 v120, v120
	v_exp_f32_e32 v121, v121
	v_add_f32_e32 v120, 1.0, v120
	v_add_f32_e32 v121, 1.0, v121
	v_rcp_f32_e32 v120, v120
	v_rcp_f32_e32 v121, v121
	s_nop 0
	v_pk_mul_f32 v[114:115], v[114:115], v[120:121]
	s_nop 0
	v_pk_mul_f32 v[120:121], v[116:117], v[114:115]
	v_cvt_pk_bf16_f32 v116, v118, v119
	v_lshrrev_b32_e32 v118, 8, v187
	v_mad_i32_i24 v118, v118, 44, v161
	v_ashrrev_i32_e32 v119, 31, v118
	v_cvt_pk_bf16_f32 v117, v120, v121
	v_lshlrev_b64 v[118:119], 15, v[118:119]
	v_lshlrev_b32_e32 v120, 7, v187
	v_lshl_add_u64 v[118:119], s[14:15], 0, v[118:119]
	v_and_b32_e32 v120, 0x7f80, v120
	v_mov_b32_e32 v121, v0
	v_lshl_add_u64 v[118:119], v[118:119], 0, v[120:121]
	v_cvt_pk_bf16_f32 v114, v122, v123
	v_cvt_pk_bf16_f32 v115, v124, v125
	v_lshl_add_u64 v[118:119], v[118:119], 0, v[130:131]
	global_store_dwordx4 v[118:119], v[114:117], off nt
	v_pk_fma_f32 v[110:111], v[110:111], v[178:179], v[98:99] op_sel_hi:[1,0,1]
	v_pk_fma_f32 v[106:107], v[106:107], v[178:179], v[102:103] op_sel_hi:[1,0,1]
	v_mul_f32_e32 v114, 0xbfb8aa3b, v110
	v_mul_f32_e32 v115, 0xbfb8aa3b, v111
	v_exp_f32_e32 v114, v114
	v_exp_f32_e32 v115, v115
	v_pk_fma_f32 v[108:109], v[108:109], v[178:179], v[104:105] op_sel_hi:[1,0,1]
	v_pk_fma_f32 v[94:95], v[94:95], v[178:179], v[82:83] op_sel_hi:[1,0,1]
	v_add_f32_e32 v114, 1.0, v114
	v_add_f32_e32 v115, 1.0, v115
	v_rcp_f32_e32 v114, v114
	v_rcp_f32_e32 v115, v115
	v_pk_fma_f32 v[90:91], v[90:91], v[178:179], v[86:87] op_sel_hi:[1,0,1]
	v_pk_fma_f32 v[92:93], v[92:93], v[178:179], v[88:89] op_sel_hi:[1,0,1]
	v_pk_mul_f32 v[110:111], v[110:111], v[114:115]
	s_nop 0
	v_pk_mul_f32 v[106:107], v[106:107], v[110:111]
	v_pk_fma_f32 v[110:111], v[112:113], v[178:179], v[100:101] op_sel_hi:[1,0,1]
	s_nop 0
	v_mul_f32_e32 v112, 0xbfb8aa3b, v110
	v_mul_f32_e32 v113, 0xbfb8aa3b, v111
	v_exp_f32_e32 v112, v112
	v_exp_f32_e32 v113, v113
	v_add_f32_e32 v112, 1.0, v112
	v_add_f32_e32 v113, 1.0, v113
	v_rcp_f32_e32 v112, v112
	v_rcp_f32_e32 v113, v113
	s_nop 0
	v_pk_mul_f32 v[110:111], v[110:111], v[112:113]
	s_nop 0
	v_pk_mul_f32 v[108:109], v[108:109], v[110:111]
	v_mul_f32_e32 v110, 0xbfb8aa3b, v94
	v_mul_f32_e32 v111, 0xbfb8aa3b, v95
	v_exp_f32_e32 v110, v110
	v_exp_f32_e32 v111, v111
	v_add_f32_e32 v110, 1.0, v110
	v_add_f32_e32 v111, 1.0, v111
	v_rcp_f32_e32 v110, v110
	v_rcp_f32_e32 v111, v111
	s_nop 0
	v_pk_mul_f32 v[94:95], v[94:95], v[110:111]
	s_nop 0
	v_pk_mul_f32 v[94:95], v[90:91], v[94:95]
	v_pk_fma_f32 v[90:91], v[96:97], v[178:179], v[84:85] op_sel_hi:[1,0,1]
	s_nop 0
	v_mul_f32_e32 v96, 0xbfb8aa3b, v90
	v_mul_f32_e32 v97, 0xbfb8aa3b, v91
	v_exp_f32_e32 v96, v96
	v_exp_f32_e32 v97, v97
	v_add_f32_e32 v96, 1.0, v96
	v_add_f32_e32 v97, 1.0, v97
	v_rcp_f32_e32 v96, v96
	v_rcp_f32_e32 v97, v97
	s_nop 0
	v_pk_mul_f32 v[90:91], v[90:91], v[96:97]
	s_nop 0
	v_pk_mul_f32 v[96:97], v[92:93], v[90:91]
	v_cvt_pk_bf16_f32 v92, v94, v95
	v_lshrrev_b32_e32 v94, 8, v185
	v_mad_i32_i24 v94, v94, 44, v161
	v_ashrrev_i32_e32 v95, 31, v94
	v_cvt_pk_bf16_f32 v93, v96, v97
	v_lshlrev_b64 v[94:95], 15, v[94:95]
	v_lshlrev_b32_e32 v96, 7, v185
	v_lshl_add_u64 v[94:95], s[14:15], 0, v[94:95]
	v_and_b32_e32 v96, 0x7f80, v96
	v_mov_b32_e32 v97, v0
	v_lshl_add_u64 v[94:95], v[94:95], 0, v[96:97]
	v_cvt_pk_bf16_f32 v90, v106, v107
	v_cvt_pk_bf16_f32 v91, v108, v109
	v_lshl_add_u64 v[94:95], v[94:95], 0, v[130:131]
	global_store_dwordx4 v[94:95], v[90:93], off nt
	v_pk_fma_f32 v[78:79], v[78:79], v[176:177], v[98:99] op_sel_hi:[1,0,1]
	v_pk_fma_f32 v[74:75], v[74:75], v[176:177], v[102:103] op_sel_hi:[1,0,1]
	v_mul_f32_e32 v90, 0xbfb8aa3b, v78
	v_mul_f32_e32 v91, 0xbfb8aa3b, v79
	v_exp_f32_e32 v90, v90
	v_exp_f32_e32 v91, v91
	v_pk_fma_f32 v[76:77], v[76:77], v[176:177], v[104:105] op_sel_hi:[1,0,1]
	v_pk_fma_f32 v[70:71], v[70:71], v[176:177], v[82:83] op_sel_hi:[1,0,1]
	v_add_f32_e32 v90, 1.0, v90
	v_add_f32_e32 v91, 1.0, v91
	v_rcp_f32_e32 v90, v90
	v_rcp_f32_e32 v91, v91
	v_pk_fma_f32 v[66:67], v[66:67], v[176:177], v[86:87] op_sel_hi:[1,0,1]
	v_pk_fma_f32 v[68:69], v[68:69], v[176:177], v[88:89] op_sel_hi:[1,0,1]
	v_pk_mul_f32 v[78:79], v[78:79], v[90:91]
	s_nop 0
	v_pk_mul_f32 v[74:75], v[74:75], v[78:79]
	v_pk_fma_f32 v[78:79], v[80:81], v[176:177], v[100:101] op_sel_hi:[1,0,1]
	s_nop 0
	v_mul_f32_e32 v80, 0xbfb8aa3b, v78
	v_mul_f32_e32 v81, 0xbfb8aa3b, v79
	v_exp_f32_e32 v80, v80
	v_exp_f32_e32 v81, v81
	v_add_f32_e32 v80, 1.0, v80
	v_add_f32_e32 v81, 1.0, v81
	v_rcp_f32_e32 v80, v80
	v_rcp_f32_e32 v81, v81
	s_nop 0
	v_pk_mul_f32 v[78:79], v[78:79], v[80:81]
	s_nop 0
	v_pk_mul_f32 v[76:77], v[76:77], v[78:79]
	v_mul_f32_e32 v78, 0xbfb8aa3b, v70
	v_mul_f32_e32 v79, 0xbfb8aa3b, v71
	v_exp_f32_e32 v78, v78
	v_exp_f32_e32 v79, v79
	v_add_f32_e32 v78, 1.0, v78
	v_add_f32_e32 v79, 1.0, v79
	v_rcp_f32_e32 v78, v78
	v_rcp_f32_e32 v79, v79
	s_nop 0
	v_pk_mul_f32 v[70:71], v[70:71], v[78:79]
	s_nop 0
	v_pk_mul_f32 v[70:71], v[66:67], v[70:71]
	v_pk_fma_f32 v[66:67], v[72:73], v[176:177], v[84:85] op_sel_hi:[1,0,1]
	s_nop 0
	v_mul_f32_e32 v72, 0xbfb8aa3b, v66
	v_mul_f32_e32 v73, 0xbfb8aa3b, v67
	v_exp_f32_e32 v72, v72
	v_exp_f32_e32 v73, v73
	v_add_f32_e32 v72, 1.0, v72
	v_add_f32_e32 v73, 1.0, v73
	v_rcp_f32_e32 v72, v72
	v_rcp_f32_e32 v73, v73
	s_nop 0
	v_pk_mul_f32 v[66:67], v[66:67], v[72:73]
	s_nop 0
	v_pk_mul_f32 v[72:73], v[68:69], v[66:67]
	v_cvt_pk_bf16_f32 v68, v70, v71
	v_lshrrev_b32_e32 v70, 8, v183
	v_mad_i32_i24 v70, v70, 44, v161
	v_ashrrev_i32_e32 v71, 31, v70
	v_cvt_pk_bf16_f32 v69, v72, v73
	v_lshlrev_b64 v[70:71], 15, v[70:71]
	v_lshlrev_b32_e32 v72, 7, v183
	v_lshl_add_u64 v[70:71], s[14:15], 0, v[70:71]
	v_and_b32_e32 v72, 0x7f80, v72
	v_mov_b32_e32 v73, v0
	v_lshl_add_u64 v[70:71], v[70:71], 0, v[72:73]
	v_cvt_pk_bf16_f32 v66, v74, v75
	v_cvt_pk_bf16_f32 v67, v76, v77
	v_lshl_add_u64 v[70:71], v[70:71], 0, v[130:131]
	global_store_dwordx4 v[70:71], v[66:69], off nt
	v_pk_fma_f32 v[62:63], v[62:63], v[174:175], v[98:99] op_sel_hi:[1,0,1]
	v_pk_fma_f32 v[58:59], v[58:59], v[174:175], v[102:103] op_sel_hi:[1,0,1]
	v_mul_f32_e32 v66, 0xbfb8aa3b, v62
	v_mul_f32_e32 v67, 0xbfb8aa3b, v63
	v_exp_f32_e32 v66, v66
	v_exp_f32_e32 v67, v67
	v_pk_fma_f32 v[60:61], v[60:61], v[174:175], v[104:105] op_sel_hi:[1,0,1]
	v_pk_fma_f32 v[54:55], v[54:55], v[174:175], v[82:83] op_sel_hi:[1,0,1]
	v_add_f32_e32 v66, 1.0, v66
	v_add_f32_e32 v67, 1.0, v67
	v_rcp_f32_e32 v66, v66
	v_rcp_f32_e32 v67, v67
	v_pk_fma_f32 v[50:51], v[50:51], v[174:175], v[86:87] op_sel_hi:[1,0,1]
	v_pk_fma_f32 v[52:53], v[52:53], v[174:175], v[88:89] op_sel_hi:[1,0,1]
	v_pk_mul_f32 v[62:63], v[62:63], v[66:67]
	s_nop 0
	v_pk_mul_f32 v[58:59], v[58:59], v[62:63]
	v_pk_fma_f32 v[62:63], v[64:65], v[174:175], v[100:101] op_sel_hi:[1,0,1]
	s_nop 0
	v_mul_f32_e32 v64, 0xbfb8aa3b, v62
	v_mul_f32_e32 v65, 0xbfb8aa3b, v63
	v_exp_f32_e32 v64, v64
	v_exp_f32_e32 v65, v65
	v_add_f32_e32 v64, 1.0, v64
	v_add_f32_e32 v65, 1.0, v65
	v_rcp_f32_e32 v64, v64
	v_rcp_f32_e32 v65, v65
	s_nop 0
	v_pk_mul_f32 v[62:63], v[62:63], v[64:65]
	s_nop 0
	v_pk_mul_f32 v[60:61], v[60:61], v[62:63]
	v_mul_f32_e32 v62, 0xbfb8aa3b, v54
	v_mul_f32_e32 v63, 0xbfb8aa3b, v55
	v_exp_f32_e32 v62, v62
	v_exp_f32_e32 v63, v63
	v_add_f32_e32 v62, 1.0, v62
	v_add_f32_e32 v63, 1.0, v63
	v_rcp_f32_e32 v62, v62
	v_rcp_f32_e32 v63, v63
	s_nop 0
	v_pk_mul_f32 v[54:55], v[54:55], v[62:63]
	s_nop 0
	v_pk_mul_f32 v[54:55], v[50:51], v[54:55]
	v_pk_fma_f32 v[50:51], v[56:57], v[174:175], v[84:85] op_sel_hi:[1,0,1]
	s_nop 0
	v_mul_f32_e32 v56, 0xbfb8aa3b, v50
	v_mul_f32_e32 v57, 0xbfb8aa3b, v51
	v_exp_f32_e32 v56, v56
	v_exp_f32_e32 v57, v57
	v_add_f32_e32 v56, 1.0, v56
	v_add_f32_e32 v57, 1.0, v57
	v_rcp_f32_e32 v56, v56
	v_rcp_f32_e32 v57, v57
	s_nop 0
	v_pk_mul_f32 v[50:51], v[50:51], v[56:57]
	s_nop 0
	v_pk_mul_f32 v[56:57], v[52:53], v[50:51]
	v_cvt_pk_bf16_f32 v52, v54, v55
	v_lshrrev_b32_e32 v54, 8, v181
	v_mad_i32_i24 v54, v54, 44, v161
	v_ashrrev_i32_e32 v55, 31, v54
	v_cvt_pk_bf16_f32 v53, v56, v57
	v_lshlrev_b64 v[54:55], 15, v[54:55]
	v_lshlrev_b32_e32 v56, 7, v181
	v_lshl_add_u64 v[54:55], s[14:15], 0, v[54:55]
	v_and_b32_e32 v56, 0x7f80, v56
	v_mov_b32_e32 v57, v0
	v_lshl_add_u64 v[54:55], v[54:55], 0, v[56:57]
	v_cvt_pk_bf16_f32 v50, v58, v59
	v_cvt_pk_bf16_f32 v51, v60, v61
	v_lshl_add_u64 v[54:55], v[54:55], 0, v[130:131]
	global_store_dwordx4 v[54:55], v[50:53], off nt
	v_pk_fma_f32 v[46:47], v[46:47], v[172:173], v[98:99] op_sel_hi:[1,0,1]
	v_pk_fma_f32 v[42:43], v[42:43], v[172:173], v[102:103] op_sel_hi:[1,0,1]
	v_mul_f32_e32 v50, 0xbfb8aa3b, v46
	v_mul_f32_e32 v51, 0xbfb8aa3b, v47
	v_exp_f32_e32 v50, v50
	v_exp_f32_e32 v51, v51
	v_pk_fma_f32 v[44:45], v[44:45], v[172:173], v[104:105] op_sel_hi:[1,0,1]
	v_pk_fma_f32 v[38:39], v[38:39], v[172:173], v[82:83] op_sel_hi:[1,0,1]
	v_add_f32_e32 v50, 1.0, v50
	v_add_f32_e32 v51, 1.0, v51
	v_rcp_f32_e32 v50, v50
	v_rcp_f32_e32 v51, v51
	v_pk_fma_f32 v[34:35], v[34:35], v[172:173], v[86:87] op_sel_hi:[1,0,1]
	v_pk_fma_f32 v[36:37], v[36:37], v[172:173], v[88:89] op_sel_hi:[1,0,1]
	v_pk_mul_f32 v[46:47], v[46:47], v[50:51]
	s_nop 0
	v_pk_mul_f32 v[42:43], v[42:43], v[46:47]
	v_pk_fma_f32 v[46:47], v[48:49], v[172:173], v[100:101] op_sel_hi:[1,0,1]
	s_nop 0
	v_mul_f32_e32 v48, 0xbfb8aa3b, v46
	v_mul_f32_e32 v49, 0xbfb8aa3b, v47
	v_exp_f32_e32 v48, v48
	v_exp_f32_e32 v49, v49
	v_add_f32_e32 v48, 1.0, v48
	v_add_f32_e32 v49, 1.0, v49
	v_rcp_f32_e32 v48, v48
	v_rcp_f32_e32 v49, v49
	s_nop 0
	v_pk_mul_f32 v[46:47], v[46:47], v[48:49]
	s_nop 0
	v_pk_mul_f32 v[44:45], v[44:45], v[46:47]
	v_mul_f32_e32 v46, 0xbfb8aa3b, v38
	v_mul_f32_e32 v47, 0xbfb8aa3b, v39
	v_exp_f32_e32 v46, v46
	v_exp_f32_e32 v47, v47
	v_add_f32_e32 v46, 1.0, v46
	v_add_f32_e32 v47, 1.0, v47
	v_rcp_f32_e32 v46, v46
	v_rcp_f32_e32 v47, v47
	s_nop 0
	v_pk_mul_f32 v[38:39], v[38:39], v[46:47]
	s_nop 0
	v_pk_mul_f32 v[38:39], v[34:35], v[38:39]
	v_pk_fma_f32 v[34:35], v[40:41], v[172:173], v[84:85] op_sel_hi:[1,0,1]
	s_nop 0
	v_mul_f32_e32 v40, 0xbfb8aa3b, v34
	v_mul_f32_e32 v41, 0xbfb8aa3b, v35
	v_exp_f32_e32 v40, v40
	v_exp_f32_e32 v41, v41
	v_add_f32_e32 v40, 1.0, v40
	v_add_f32_e32 v41, 1.0, v41
	v_rcp_f32_e32 v40, v40
	v_rcp_f32_e32 v41, v41
	s_nop 0
	v_pk_mul_f32 v[34:35], v[34:35], v[40:41]
	s_nop 0
	v_pk_mul_f32 v[40:41], v[36:37], v[34:35]
	v_cvt_pk_bf16_f32 v36, v38, v39
	v_lshrrev_b32_e32 v38, 8, v179
	v_mad_i32_i24 v38, v38, 44, v161
	v_ashrrev_i32_e32 v39, 31, v38
	v_cvt_pk_bf16_f32 v37, v40, v41
	v_lshlrev_b64 v[38:39], 15, v[38:39]
	v_lshlrev_b32_e32 v40, 7, v179
	v_lshl_add_u64 v[38:39], s[14:15], 0, v[38:39]
	v_and_b32_e32 v40, 0x7f80, v40
	v_mov_b32_e32 v41, v0
	v_lshl_add_u64 v[38:39], v[38:39], 0, v[40:41]
	v_cvt_pk_bf16_f32 v34, v42, v43
	v_cvt_pk_bf16_f32 v35, v44, v45
	v_lshl_add_u64 v[38:39], v[38:39], 0, v[130:131]
	global_store_dwordx4 v[38:39], v[34:37], off nt
	v_pk_fma_f32 v[30:31], v[30:31], v[158:159], v[98:99] op_sel_hi:[1,0,1]
	v_pk_fma_f32 v[26:27], v[26:27], v[158:159], v[102:103] op_sel_hi:[1,0,1]
	v_mul_f32_e32 v34, 0xbfb8aa3b, v30
	v_mul_f32_e32 v35, 0xbfb8aa3b, v31
	v_exp_f32_e32 v34, v34
	v_exp_f32_e32 v35, v35
	v_pk_fma_f32 v[28:29], v[28:29], v[158:159], v[104:105] op_sel_hi:[1,0,1]
	v_pk_fma_f32 v[22:23], v[22:23], v[158:159], v[82:83] op_sel_hi:[1,0,1]
	v_add_f32_e32 v34, 1.0, v34
	v_add_f32_e32 v35, 1.0, v35
	v_rcp_f32_e32 v34, v34
	v_rcp_f32_e32 v35, v35
	v_pk_fma_f32 v[18:19], v[18:19], v[158:159], v[86:87] op_sel_hi:[1,0,1]
	v_pk_fma_f32 v[20:21], v[20:21], v[158:159], v[88:89] op_sel_hi:[1,0,1]
	v_pk_mul_f32 v[30:31], v[30:31], v[34:35]
	s_nop 0
	v_pk_mul_f32 v[26:27], v[26:27], v[30:31]
	v_pk_fma_f32 v[30:31], v[32:33], v[158:159], v[100:101] op_sel_hi:[1,0,1]
	s_nop 0
	v_mul_f32_e32 v32, 0xbfb8aa3b, v30
	v_mul_f32_e32 v33, 0xbfb8aa3b, v31
	v_exp_f32_e32 v32, v32
	v_exp_f32_e32 v33, v33
	v_add_f32_e32 v32, 1.0, v32
	v_add_f32_e32 v33, 1.0, v33
	v_rcp_f32_e32 v32, v32
	v_rcp_f32_e32 v33, v33
	s_nop 0
	v_pk_mul_f32 v[30:31], v[30:31], v[32:33]
	s_nop 0
	v_pk_mul_f32 v[28:29], v[28:29], v[30:31]
	v_mul_f32_e32 v30, 0xbfb8aa3b, v22
	v_mul_f32_e32 v31, 0xbfb8aa3b, v23
	v_exp_f32_e32 v30, v30
	v_exp_f32_e32 v31, v31
	v_add_f32_e32 v30, 1.0, v30
	v_add_f32_e32 v31, 1.0, v31
	v_rcp_f32_e32 v30, v30
	v_rcp_f32_e32 v31, v31
	s_nop 0
	v_pk_mul_f32 v[22:23], v[22:23], v[30:31]
	s_nop 0
	v_pk_mul_f32 v[22:23], v[18:19], v[22:23]
	v_pk_fma_f32 v[18:19], v[24:25], v[158:159], v[84:85] op_sel_hi:[1,0,1]
	s_nop 0
	v_mul_f32_e32 v24, 0xbfb8aa3b, v18
	v_mul_f32_e32 v25, 0xbfb8aa3b, v19
	v_exp_f32_e32 v24, v24
	v_exp_f32_e32 v25, v25
	v_add_f32_e32 v24, 1.0, v24
	v_add_f32_e32 v25, 1.0, v25
	v_rcp_f32_e32 v24, v24
	v_rcp_f32_e32 v25, v25
	s_nop 0
	v_pk_mul_f32 v[18:19], v[18:19], v[24:25]
	s_nop 0
	v_pk_mul_f32 v[24:25], v[20:21], v[18:19]
	v_cvt_pk_bf16_f32 v20, v22, v23
	v_lshrrev_b32_e32 v22, 8, v177
	v_mad_i32_i24 v22, v22, 44, v161
	v_ashrrev_i32_e32 v23, 31, v22
	v_cvt_pk_bf16_f32 v21, v24, v25
	v_lshlrev_b64 v[22:23], 15, v[22:23]
	v_lshlrev_b32_e32 v24, 7, v177
	v_lshl_add_u64 v[22:23], s[14:15], 0, v[22:23]
	v_and_b32_e32 v24, 0x7f80, v24
	v_mov_b32_e32 v25, v0
	v_lshl_add_u64 v[22:23], v[22:23], 0, v[24:25]
	v_cvt_pk_bf16_f32 v18, v26, v27
	v_cvt_pk_bf16_f32 v19, v28, v29
	v_lshl_add_u64 v[22:23], v[22:23], 0, v[130:131]
	global_store_dwordx4 v[22:23], v[18:21], off nt
	v_pk_fma_f32 v[14:15], v[14:15], v[160:161], v[98:99] op_sel_hi:[1,0,1]
	v_pk_fma_f32 v[10:11], v[10:11], v[160:161], v[102:103] op_sel_hi:[1,0,1]
	v_mul_f32_e32 v18, 0xbfb8aa3b, v14
	v_mul_f32_e32 v19, 0xbfb8aa3b, v15
	v_exp_f32_e32 v18, v18
	v_exp_f32_e32 v19, v19
	v_pk_fma_f32 v[12:13], v[12:13], v[160:161], v[104:105] op_sel_hi:[1,0,1]
	v_pk_fma_f32 v[6:7], v[6:7], v[160:161], v[82:83] op_sel_hi:[1,0,1]
	v_add_f32_e32 v18, 1.0, v18
	v_add_f32_e32 v19, 1.0, v19
	v_rcp_f32_e32 v18, v18
	v_rcp_f32_e32 v19, v19
	v_pk_fma_f32 v[2:3], v[2:3], v[160:161], v[86:87] op_sel_hi:[1,0,1]
	v_pk_fma_f32 v[4:5], v[4:5], v[160:161], v[88:89] op_sel_hi:[1,0,1]
	s_and_b64 vcc, exec, s[36:37]
	v_pk_mul_f32 v[14:15], v[14:15], v[18:19]
	s_mov_b32 s42, s4
	v_pk_mul_f32 v[10:11], v[10:11], v[14:15]
	v_pk_fma_f32 v[14:15], v[16:17], v[160:161], v[100:101] op_sel_hi:[1,0,1]
	s_mov_b32 s12, s6
	v_mul_f32_e32 v16, 0xbfb8aa3b, v14
	v_mul_f32_e32 v17, 0xbfb8aa3b, v15
	v_exp_f32_e32 v16, v16
	v_exp_f32_e32 v17, v17
	s_mov_b64 s[16:17], s[10:11]
	v_add_f32_e32 v16, 1.0, v16
	v_add_f32_e32 v17, 1.0, v17
	v_rcp_f32_e32 v16, v16
	v_rcp_f32_e32 v17, v17
	s_nop 0
	v_pk_mul_f32 v[14:15], v[14:15], v[16:17]
	s_nop 0
	v_pk_mul_f32 v[12:13], v[12:13], v[14:15]
	v_mul_f32_e32 v14, 0xbfb8aa3b, v6
	v_mul_f32_e32 v15, 0xbfb8aa3b, v7
	v_exp_f32_e32 v14, v14
	v_exp_f32_e32 v15, v15
	v_add_f32_e32 v14, 1.0, v14
	v_add_f32_e32 v15, 1.0, v15
	v_rcp_f32_e32 v14, v14
	v_rcp_f32_e32 v15, v15
	s_nop 0
	v_pk_mul_f32 v[6:7], v[6:7], v[14:15]
	s_nop 0
	v_pk_mul_f32 v[6:7], v[2:3], v[6:7]
	v_pk_fma_f32 v[2:3], v[8:9], v[160:161], v[84:85] op_sel_hi:[1,0,1]
	s_nop 0
	v_mul_f32_e32 v8, 0xbfb8aa3b, v2
	v_mul_f32_e32 v9, 0xbfb8aa3b, v3
	v_exp_f32_e32 v8, v8
	v_exp_f32_e32 v9, v9
	v_add_f32_e32 v8, 1.0, v8
	v_add_f32_e32 v9, 1.0, v9
	v_rcp_f32_e32 v8, v8
	v_rcp_f32_e32 v9, v9
	s_nop 0
	v_pk_mul_f32 v[2:3], v[2:3], v[8:9]
	s_nop 0
	v_pk_mul_f32 v[8:9], v[4:5], v[2:3]
	v_cvt_pk_bf16_f32 v4, v6, v7
	v_lshrrev_b32_e32 v6, 8, v175
	v_mad_i32_i24 v6, v6, 44, v161
	v_ashrrev_i32_e32 v7, 31, v6
	v_cvt_pk_bf16_f32 v5, v8, v9
	v_lshlrev_b64 v[6:7], 15, v[6:7]
	v_lshlrev_b32_e32 v8, 7, v175
	v_lshl_add_u64 v[6:7], s[14:15], 0, v[6:7]
	v_and_b32_e32 v8, 0x7f80, v8
	v_mov_b32_e32 v9, v0
	v_lshl_add_u64 v[6:7], v[6:7], 0, v[8:9]
	v_cvt_pk_bf16_f32 v2, v10, v11
	v_cvt_pk_bf16_f32 v3, v12, v13
	v_lshl_add_u64 v[6:7], v[6:7], 0, v[130:131]
	s_mov_b64 s[14:15], s[8:9]
	global_store_dwordx4 v[6:7], v[2:5], off nt
	s_cbranch_vccnz .LBB0_167

.LBB0_558:
	s_lshl_b32 s5, s12, 8
	v_mov_b32_e32 v82, v171
	v_mov_b32_e32 v83, v1
	s_add_i32 s5, s5, s31
	s_nop 0
	v_add_u32_e32 v182, s5, v82
	s_lshl_b32 s5, s42, 7
	s_or_b32 s5, s5, s34
	v_lshl_add_u32 v186, v83, 3, s5
	s_ashr_i32 s5, s12, 5
	s_mul_hi_i32 s7, s5, 0x5800
	s_mulk_i32 s5, 0x5800
	s_add_u32 s14, s28, s5
	s_addc_u32 s15, s29, s7
	v_ashrrev_i32_e32 v187, 31, v186
	v_lshl_add_u64 v[86:87], v[186:187], 2, s[14:15]
	s_mov_b64 s[14:15], 0x2c00
	s_movk_i32 s5, 0x2000
	global_load_dwordx4 v[82:85], v[86:87], off offset:16
	global_load_dwordx4 v[98:101], v[86:87], off
	v_lshl_add_u64 v[88:89], v[86:87], 0, s[14:15]
	v_add_co_u32_e32 v86, vcc, s5, v86
	v_ashrrev_i32_e32 v183, 31, v182
	s_nop 0
	v_addc_co_u32_e32 v87, vcc, 0, v87, vcc
	v_lshl_add_u64 v[160:161], v[182:183], 2, s[0:1]
	global_load_dwordx4 v[102:105], v[86:87], off offset:3072
	s_nop 0
	global_load_dwordx4 v[86:89], v[88:89], off offset:16
	v_add_u32_e32 v187, 16, v182
	global_load_dword v184, v[160:161], off
	global_load_dword v180, v[160:161], off offset:64
	global_load_dword v178, v[160:161], off offset:128
	global_load_dword v176, v[160:161], off offset:192
	global_load_dword v174, v[160:161], off offset:512
	global_load_dword v172, v[160:161], off offset:576
	global_load_dword v175, v[160:161], off offset:640
	global_load_dword v160, v[160:161], off offset:704
	v_add_u32_e32 v185, 32, v182
	v_add_u32_e32 v183, 48, v182
	v_add_u32_e32 v181, 0x80, v182
	v_add_u32_e32 v179, 0x90, v182
	v_add_u32_e32 v177, 0xa0, v182
	s_waitcnt vmcnt(0)
	v_fmamk_f32 v158, v184, 0x3a800000, v223
	v_cmp_gt_f32_e32 vcc, s95, v158
	v_mul_f32_e32 v168, 0x4b800000, v158
	s_nop 0
	v_cndmask_b32_e32 v158, v158, v168, vcc
	v_rsq_f32_e32 v158, v158
	s_nop 0
	v_mul_f32_e32 v168, 0x45800000, v158
	v_cndmask_b32_e32 v184, v158, v168, vcc
	v_fmamk_f32 v158, v180, 0x3a800000, v223
	v_cmp_gt_f32_e32 vcc, s95, v158
	v_mul_f32_e32 v168, 0x4b800000, v158
	s_nop 0
	v_cndmask_b32_e32 v158, v158, v168, vcc
	v_rsq_f32_e32 v158, v158
	s_nop 0
	v_mul_f32_e32 v168, 0x45800000, v158
	v_cndmask_b32_e32 v180, v158, v168, vcc
	v_fmamk_f32 v158, v178, 0x3a800000, v223
	v_cmp_gt_f32_e32 vcc, s95, v158
	v_mul_f32_e32 v168, 0x4b800000, v158
	s_nop 0
	v_cndmask_b32_e32 v158, v158, v168, vcc
	v_rsq_f32_e32 v158, v158
	s_nop 0
	v_mul_f32_e32 v168, 0x45800000, v158
	v_cndmask_b32_e32 v178, v158, v168, vcc
	v_fmamk_f32 v158, v176, 0x3a800000, v223
	v_cmp_gt_f32_e32 vcc, s95, v158
	v_mul_f32_e32 v168, 0x4b800000, v158
	s_nop 0
	v_cndmask_b32_e32 v158, v158, v168, vcc
	v_rsq_f32_e32 v158, v158
	s_nop 0
	v_mul_f32_e32 v168, 0x45800000, v158
	v_cndmask_b32_e32 v176, v158, v168, vcc
	v_fmamk_f32 v158, v174, 0x3a800000, v223
	v_cmp_gt_f32_e32 vcc, s95, v158
	v_mul_f32_e32 v168, 0x4b800000, v158
	s_nop 0
	v_cndmask_b32_e32 v158, v158, v168, vcc
	v_rsq_f32_e32 v158, v158
	s_nop 0
	v_mul_f32_e32 v168, 0x45800000, v158
	v_cndmask_b32_e32 v174, v158, v168, vcc
	v_fmamk_f32 v158, v172, 0x3a800000, v223
	v_cmp_gt_f32_e32 vcc, s95, v158
	v_mul_f32_e32 v168, 0x4b800000, v158
	s_nop 0
	v_cndmask_b32_e32 v158, v158, v168, vcc
	v_rsq_f32_e32 v158, v158
	s_nop 0
	v_mul_f32_e32 v168, 0x45800000, v158
	v_cndmask_b32_e32 v172, v158, v168, vcc
	v_fmamk_f32 v158, v175, 0x3a800000, v223
	v_add_u32_e32 v175, 0xb0, v182
	v_cmp_gt_f32_e32 vcc, s95, v158
	v_mul_f32_e32 v168, 0x4b800000, v158
	v_fmamk_f32 v160, v160, 0x3a800000, v223
	v_cndmask_b32_e32 v158, v158, v168, vcc
	v_rsq_f32_e32 v158, v158
	v_mul_f32_e32 v161, 0x4b800000, v160
	v_mul_f32_e32 v168, 0x45800000, v158
	v_cndmask_b32_e32 v158, v158, v168, vcc
	v_cmp_gt_f32_e32 vcc, s95, v160
	s_nop 1
	v_cndmask_b32_e32 v160, v160, v161, vcc
	v_rsq_f32_e32 v160, v160
	s_nop 0
	v_mul_f32_e32 v161, 0x45800000, v160
	v_cndmask_b32_e32 v160, v160, v161, vcc
	v_ashrrev_i32_e32 v161, 6, v186
	v_and_b32_e32 v186, 56, v186
	v_pk_fma_f32 v[138:139], v[138:139], v[184:185], v[98:99] op_sel_hi:[1,0,1]
	v_pk_fma_f32 v[142:143], v[142:143], v[184:185], v[102:103] op_sel_hi:[1,0,1]
	v_mul_f32_e32 v168, 0xbfb8aa3b, v138
	v_mul_f32_e32 v169, 0xbfb8aa3b, v139
	v_exp_f32_e32 v168, v168
	v_exp_f32_e32 v169, v169
	v_pk_fma_f32 v[140:141], v[140:141], v[184:185], v[100:101] op_sel_hi:[1,0,1]
	v_pk_fma_f32 v[134:135], v[134:135], v[184:185], v[82:83] op_sel_hi:[1,0,1]
	v_add_f32_e32 v168, 1.0, v168
	v_add_f32_e32 v169, 1.0, v169
	v_rcp_f32_e32 v168, v168
	v_rcp_f32_e32 v169, v169
	v_pk_fma_f32 v[130:131], v[130:131], v[184:185], v[86:87] op_sel_hi:[1,0,1]
	v_pk_fma_f32 v[132:133], v[132:133], v[184:185], v[88:89] op_sel_hi:[1,0,1]
	v_readlane_b32 s14, v254, 27
	v_pk_mul_f32 v[138:139], v[138:139], v[168:169]
	v_readlane_b32 s15, v254, 28
	v_pk_mul_f32 v[138:139], v[142:143], v[138:139]
	v_pk_fma_f32 v[142:143], v[144:145], v[184:185], v[104:105] op_sel_hi:[1,0,1]
	v_mul_f32_e32 v144, 0xbfb8aa3b, v140
	v_mul_f32_e32 v145, 0xbfb8aa3b, v141
	v_exp_f32_e32 v144, v144
	v_exp_f32_e32 v145, v145
	v_add_f32_e32 v144, 1.0, v144
	v_add_f32_e32 v145, 1.0, v145
	v_rcp_f32_e32 v144, v144
	v_rcp_f32_e32 v145, v145
	s_nop 0
	v_pk_mul_f32 v[140:141], v[140:141], v[144:145]
	s_nop 0
	v_pk_mul_f32 v[140:141], v[142:143], v[140:141]
	v_mul_f32_e32 v142, 0xbfb8aa3b, v134
	v_mul_f32_e32 v143, 0xbfb8aa3b, v135
	v_exp_f32_e32 v142, v142
	v_exp_f32_e32 v143, v143
	v_add_f32_e32 v142, 1.0, v142
	v_add_f32_e32 v143, 1.0, v143
	v_rcp_f32_e32 v142, v142
	v_rcp_f32_e32 v143, v143
	s_nop 0
	v_pk_mul_f32 v[134:135], v[134:135], v[142:143]
	s_nop 0
	v_pk_mul_f32 v[130:131], v[130:131], v[134:135]
	v_pk_fma_f32 v[134:135], v[136:137], v[184:185], v[84:85] op_sel_hi:[1,0,1]
	s_nop 0
	v_mul_f32_e32 v136, 0xbfb8aa3b, v134
	v_mul_f32_e32 v137, 0xbfb8aa3b, v135
	v_exp_f32_e32 v136, v136
	v_exp_f32_e32 v137, v137
	v_add_f32_e32 v136, 1.0, v136
	v_add_f32_e32 v137, 1.0, v137
	v_rcp_f32_e32 v136, v136
	v_rcp_f32_e32 v137, v137
	s_nop 0
	v_pk_mul_f32 v[134:135], v[134:135], v[136:137]
	s_nop 0
	v_pk_mul_f32 v[136:137], v[132:133], v[134:135]
	v_cvt_pk_bf16_f32 v134, v130, v131
	v_lshrrev_b32_e32 v130, 8, v182
	v_mad_i32_i24 v130, v130, 44, v161
	v_ashrrev_i32_e32 v131, 31, v130
	v_cvt_pk_bf16_f32 v135, v136, v137
	v_lshlrev_b64 v[130:131], 15, v[130:131]
	v_lshlrev_b32_e32 v136, 7, v182
	v_lshl_add_u64 v[130:131], s[14:15], 0, v[130:131]
	v_and_b32_e32 v136, 0x7f80, v136
	v_mov_b32_e32 v137, v0
	v_lshl_add_u64 v[136:137], v[130:131], 0, v[136:137]
	v_lshlrev_b32_e32 v130, 1, v186
	v_mov_b32_e32 v131, v0
	v_cvt_pk_bf16_f32 v132, v138, v139
	v_cvt_pk_bf16_f32 v133, v140, v141
	v_lshl_add_u64 v[136:137], v[136:137], 0, v[130:131]
	global_store_dwordx4 v[136:137], v[132:135], off nt
	v_pk_fma_f32 v[126:127], v[126:127], v[180:181], v[98:99] op_sel_hi:[1,0,1]
	v_pk_fma_f32 v[122:123], v[122:123], v[180:181], v[102:103] op_sel_hi:[1,0,1]
	v_mul_f32_e32 v132, 0xbfb8aa3b, v126
	v_mul_f32_e32 v133, 0xbfb8aa3b, v127
	v_exp_f32_e32 v132, v132
	v_exp_f32_e32 v133, v133
	v_pk_fma_f32 v[124:125], v[124:125], v[180:181], v[104:105] op_sel_hi:[1,0,1]
	v_pk_fma_f32 v[118:119], v[118:119], v[180:181], v[82:83] op_sel_hi:[1,0,1]
	v_add_f32_e32 v132, 1.0, v132
	v_add_f32_e32 v133, 1.0, v133
	v_rcp_f32_e32 v132, v132
	v_rcp_f32_e32 v133, v133
	v_pk_fma_f32 v[114:115], v[114:115], v[180:181], v[86:87] op_sel_hi:[1,0,1]
	v_pk_fma_f32 v[116:117], v[116:117], v[180:181], v[88:89] op_sel_hi:[1,0,1]
	v_pk_mul_f32 v[126:127], v[126:127], v[132:133]
	s_nop 0
	v_pk_mul_f32 v[122:123], v[122:123], v[126:127]
	v_pk_fma_f32 v[126:127], v[128:129], v[180:181], v[100:101] op_sel_hi:[1,0,1]
	s_nop 0
	v_mul_f32_e32 v128, 0xbfb8aa3b, v126
	v_mul_f32_e32 v129, 0xbfb8aa3b, v127
	v_exp_f32_e32 v128, v128
	v_exp_f32_e32 v129, v129
	v_add_f32_e32 v128, 1.0, v128
	v_add_f32_e32 v129, 1.0, v129
	v_rcp_f32_e32 v128, v128
	v_rcp_f32_e32 v129, v129
	s_nop 0
	v_pk_mul_f32 v[126:127], v[126:127], v[128:129]
	s_nop 0
	v_pk_mul_f32 v[124:125], v[124:125], v[126:127]
	v_mul_f32_e32 v126, 0xbfb8aa3b, v118
	v_mul_f32_e32 v127, 0xbfb8aa3b, v119
	v_exp_f32_e32 v126, v126
	v_exp_f32_e32 v127, v127
	v_add_f32_e32 v126, 1.0, v126
	v_add_f32_e32 v127, 1.0, v127
	v_rcp_f32_e32 v126, v126
	v_rcp_f32_e32 v127, v127
	s_nop 0
	v_pk_mul_f32 v[118:119], v[118:119], v[126:127]
	s_nop 0
	v_pk_mul_f32 v[118:119], v[114:115], v[118:119]
	v_pk_fma_f32 v[114:115], v[120:121], v[180:181], v[84:85] op_sel_hi:[1,0,1]
	s_nop 0
	v_mul_f32_e32 v120, 0xbfb8aa3b, v114
	v_mul_f32_e32 v121, 0xbfb8aa3b, v115
	v_exp_f32_e32 v120, v120
	v_exp_f32_e32 v121, v121
	v_add_f32_e32 v120, 1.0, v120
	v_add_f32_e32 v121, 1.0, v121
	v_rcp_f32_e32 v120, v120
	v_rcp_f32_e32 v121, v121
	s_nop 0
	v_pk_mul_f32 v[114:115], v[114:115], v[120:121]
	s_nop 0
	v_pk_mul_f32 v[120:121], v[116:117], v[114:115]
	v_cvt_pk_bf16_f32 v116, v118, v119
	v_lshrrev_b32_e32 v118, 8, v187
	v_mad_i32_i24 v118, v118, 44, v161
	v_ashrrev_i32_e32 v119, 31, v118
	v_cvt_pk_bf16_f32 v117, v120, v121
	v_lshlrev_b64 v[118:119], 15, v[118:119]
	v_lshlrev_b32_e32 v120, 7, v187
	v_lshl_add_u64 v[118:119], s[14:15], 0, v[118:119]
	v_and_b32_e32 v120, 0x7f80, v120
	v_mov_b32_e32 v121, v0
	v_lshl_add_u64 v[118:119], v[118:119], 0, v[120:121]
	v_cvt_pk_bf16_f32 v114, v122, v123
	v_cvt_pk_bf16_f32 v115, v124, v125
	v_lshl_add_u64 v[118:119], v[118:119], 0, v[130:131]
	global_store_dwordx4 v[118:119], v[114:117], off nt
	v_pk_fma_f32 v[110:111], v[110:111], v[178:179], v[98:99] op_sel_hi:[1,0,1]
	v_pk_fma_f32 v[106:107], v[106:107], v[178:179], v[102:103] op_sel_hi:[1,0,1]
	v_mul_f32_e32 v114, 0xbfb8aa3b, v110
	v_mul_f32_e32 v115, 0xbfb8aa3b, v111
	v_exp_f32_e32 v114, v114
	v_exp_f32_e32 v115, v115
	v_pk_fma_f32 v[108:109], v[108:109], v[178:179], v[104:105] op_sel_hi:[1,0,1]
	v_pk_fma_f32 v[94:95], v[94:95], v[178:179], v[82:83] op_sel_hi:[1,0,1]
	v_add_f32_e32 v114, 1.0, v114
	v_add_f32_e32 v115, 1.0, v115
	v_rcp_f32_e32 v114, v114
	v_rcp_f32_e32 v115, v115
	v_pk_fma_f32 v[90:91], v[90:91], v[178:179], v[86:87] op_sel_hi:[1,0,1]
	v_pk_fma_f32 v[92:93], v[92:93], v[178:179], v[88:89] op_sel_hi:[1,0,1]
	v_pk_mul_f32 v[110:111], v[110:111], v[114:115]
	s_nop 0
	v_pk_mul_f32 v[106:107], v[106:107], v[110:111]
	v_pk_fma_f32 v[110:111], v[112:113], v[178:179], v[100:101] op_sel_hi:[1,0,1]
	s_nop 0
	v_mul_f32_e32 v112, 0xbfb8aa3b, v110
	v_mul_f32_e32 v113, 0xbfb8aa3b, v111
	v_exp_f32_e32 v112, v112
	v_exp_f32_e32 v113, v113
	v_add_f32_e32 v112, 1.0, v112
	v_add_f32_e32 v113, 1.0, v113
	v_rcp_f32_e32 v112, v112
	v_rcp_f32_e32 v113, v113
	s_nop 0
	v_pk_mul_f32 v[110:111], v[110:111], v[112:113]
	s_nop 0
	v_pk_mul_f32 v[108:109], v[108:109], v[110:111]
	v_mul_f32_e32 v110, 0xbfb8aa3b, v94
	v_mul_f32_e32 v111, 0xbfb8aa3b, v95
	v_exp_f32_e32 v110, v110
	v_exp_f32_e32 v111, v111
	v_add_f32_e32 v110, 1.0, v110
	v_add_f32_e32 v111, 1.0, v111
	v_rcp_f32_e32 v110, v110
	v_rcp_f32_e32 v111, v111
	s_nop 0
	v_pk_mul_f32 v[94:95], v[94:95], v[110:111]
	s_nop 0
	v_pk_mul_f32 v[94:95], v[90:91], v[94:95]
	v_pk_fma_f32 v[90:91], v[96:97], v[178:179], v[84:85] op_sel_hi:[1,0,1]
	s_nop 0
	v_mul_f32_e32 v96, 0xbfb8aa3b, v90
	v_mul_f32_e32 v97, 0xbfb8aa3b, v91
	v_exp_f32_e32 v96, v96
	v_exp_f32_e32 v97, v97
	v_add_f32_e32 v96, 1.0, v96
	v_add_f32_e32 v97, 1.0, v97
	v_rcp_f32_e32 v96, v96
	v_rcp_f32_e32 v97, v97
	s_nop 0
	v_pk_mul_f32 v[90:91], v[90:91], v[96:97]
	s_nop 0
	v_pk_mul_f32 v[96:97], v[92:93], v[90:91]
	v_cvt_pk_bf16_f32 v92, v94, v95
	v_lshrrev_b32_e32 v94, 8, v185
	v_mad_i32_i24 v94, v94, 44, v161
	v_ashrrev_i32_e32 v95, 31, v94
	v_cvt_pk_bf16_f32 v93, v96, v97
	v_lshlrev_b64 v[94:95], 15, v[94:95]
	v_lshlrev_b32_e32 v96, 7, v185
	v_lshl_add_u64 v[94:95], s[14:15], 0, v[94:95]
	v_and_b32_e32 v96, 0x7f80, v96
	v_mov_b32_e32 v97, v0
	v_lshl_add_u64 v[94:95], v[94:95], 0, v[96:97]
	v_cvt_pk_bf16_f32 v90, v106, v107
	v_cvt_pk_bf16_f32 v91, v108, v109
	v_lshl_add_u64 v[94:95], v[94:95], 0, v[130:131]
	global_store_dwordx4 v[94:95], v[90:93], off nt
	v_pk_fma_f32 v[78:79], v[78:79], v[176:177], v[98:99] op_sel_hi:[1,0,1]
	v_pk_fma_f32 v[74:75], v[74:75], v[176:177], v[102:103] op_sel_hi:[1,0,1]
	v_mul_f32_e32 v90, 0xbfb8aa3b, v78
	v_mul_f32_e32 v91, 0xbfb8aa3b, v79
	v_exp_f32_e32 v90, v90
	v_exp_f32_e32 v91, v91
	v_pk_fma_f32 v[76:77], v[76:77], v[176:177], v[104:105] op_sel_hi:[1,0,1]
	v_pk_fma_f32 v[70:71], v[70:71], v[176:177], v[82:83] op_sel_hi:[1,0,1]
	v_add_f32_e32 v90, 1.0, v90
	v_add_f32_e32 v91, 1.0, v91
	v_rcp_f32_e32 v90, v90
	v_rcp_f32_e32 v91, v91
	v_pk_fma_f32 v[66:67], v[66:67], v[176:177], v[86:87] op_sel_hi:[1,0,1]
	v_pk_fma_f32 v[68:69], v[68:69], v[176:177], v[88:89] op_sel_hi:[1,0,1]
	v_pk_mul_f32 v[78:79], v[78:79], v[90:91]
	s_nop 0
	v_pk_mul_f32 v[74:75], v[74:75], v[78:79]
	v_pk_fma_f32 v[78:79], v[80:81], v[176:177], v[100:101] op_sel_hi:[1,0,1]
	s_nop 0
	v_mul_f32_e32 v80, 0xbfb8aa3b, v78
	v_mul_f32_e32 v81, 0xbfb8aa3b, v79
	v_exp_f32_e32 v80, v80
	v_exp_f32_e32 v81, v81
	v_add_f32_e32 v80, 1.0, v80
	v_add_f32_e32 v81, 1.0, v81
	v_rcp_f32_e32 v80, v80
	v_rcp_f32_e32 v81, v81
	s_nop 0
	v_pk_mul_f32 v[78:79], v[78:79], v[80:81]
	s_nop 0
	v_pk_mul_f32 v[76:77], v[76:77], v[78:79]
	v_mul_f32_e32 v78, 0xbfb8aa3b, v70
	v_mul_f32_e32 v79, 0xbfb8aa3b, v71
	v_exp_f32_e32 v78, v78
	v_exp_f32_e32 v79, v79
	v_add_f32_e32 v78, 1.0, v78
	v_add_f32_e32 v79, 1.0, v79
	v_rcp_f32_e32 v78, v78
	v_rcp_f32_e32 v79, v79
	s_nop 0
	v_pk_mul_f32 v[70:71], v[70:71], v[78:79]
	s_nop 0
	v_pk_mul_f32 v[70:71], v[66:67], v[70:71]
	v_pk_fma_f32 v[66:67], v[72:73], v[176:177], v[84:85] op_sel_hi:[1,0,1]
	s_nop 0
	v_mul_f32_e32 v72, 0xbfb8aa3b, v66
	v_mul_f32_e32 v73, 0xbfb8aa3b, v67
	v_exp_f32_e32 v72, v72
	v_exp_f32_e32 v73, v73
	v_add_f32_e32 v72, 1.0, v72
	v_add_f32_e32 v73, 1.0, v73
	v_rcp_f32_e32 v72, v72
	v_rcp_f32_e32 v73, v73
	s_nop 0
	v_pk_mul_f32 v[66:67], v[66:67], v[72:73]
	s_nop 0
	v_pk_mul_f32 v[72:73], v[68:69], v[66:67]
	v_cvt_pk_bf16_f32 v68, v70, v71
	v_lshrrev_b32_e32 v70, 8, v183
	v_mad_i32_i24 v70, v70, 44, v161
	v_ashrrev_i32_e32 v71, 31, v70
	v_cvt_pk_bf16_f32 v69, v72, v73
	v_lshlrev_b64 v[70:71], 15, v[70:71]
	v_lshlrev_b32_e32 v72, 7, v183
	v_lshl_add_u64 v[70:71], s[14:15], 0, v[70:71]
	v_and_b32_e32 v72, 0x7f80, v72
	v_mov_b32_e32 v73, v0
	v_lshl_add_u64 v[70:71], v[70:71], 0, v[72:73]
	v_cvt_pk_bf16_f32 v66, v74, v75
	v_cvt_pk_bf16_f32 v67, v76, v77
	v_lshl_add_u64 v[70:71], v[70:71], 0, v[130:131]
	global_store_dwordx4 v[70:71], v[66:69], off nt
	v_pk_fma_f32 v[62:63], v[62:63], v[174:175], v[98:99] op_sel_hi:[1,0,1]
	v_pk_fma_f32 v[58:59], v[58:59], v[174:175], v[102:103] op_sel_hi:[1,0,1]
	v_mul_f32_e32 v66, 0xbfb8aa3b, v62
	v_mul_f32_e32 v67, 0xbfb8aa3b, v63
	v_exp_f32_e32 v66, v66
	v_exp_f32_e32 v67, v67
	v_pk_fma_f32 v[60:61], v[60:61], v[174:175], v[104:105] op_sel_hi:[1,0,1]
	v_pk_fma_f32 v[54:55], v[54:55], v[174:175], v[82:83] op_sel_hi:[1,0,1]
	v_add_f32_e32 v66, 1.0, v66
	v_add_f32_e32 v67, 1.0, v67
	v_rcp_f32_e32 v66, v66
	v_rcp_f32_e32 v67, v67
	v_pk_fma_f32 v[50:51], v[50:51], v[174:175], v[86:87] op_sel_hi:[1,0,1]
	v_pk_fma_f32 v[52:53], v[52:53], v[174:175], v[88:89] op_sel_hi:[1,0,1]
	v_pk_mul_f32 v[62:63], v[62:63], v[66:67]
	s_nop 0
	v_pk_mul_f32 v[58:59], v[58:59], v[62:63]
	v_pk_fma_f32 v[62:63], v[64:65], v[174:175], v[100:101] op_sel_hi:[1,0,1]
	s_nop 0
	v_mul_f32_e32 v64, 0xbfb8aa3b, v62
	v_mul_f32_e32 v65, 0xbfb8aa3b, v63
	v_exp_f32_e32 v64, v64
	v_exp_f32_e32 v65, v65
	v_add_f32_e32 v64, 1.0, v64
	v_add_f32_e32 v65, 1.0, v65
	v_rcp_f32_e32 v64, v64
	v_rcp_f32_e32 v65, v65
	s_nop 0
	v_pk_mul_f32 v[62:63], v[62:63], v[64:65]
	s_nop 0
	v_pk_mul_f32 v[60:61], v[60:61], v[62:63]
	v_mul_f32_e32 v62, 0xbfb8aa3b, v54
	v_mul_f32_e32 v63, 0xbfb8aa3b, v55
	v_exp_f32_e32 v62, v62
	v_exp_f32_e32 v63, v63
	v_add_f32_e32 v62, 1.0, v62
	v_add_f32_e32 v63, 1.0, v63
	v_rcp_f32_e32 v62, v62
	v_rcp_f32_e32 v63, v63
	s_nop 0
	v_pk_mul_f32 v[54:55], v[54:55], v[62:63]
	s_nop 0
	v_pk_mul_f32 v[54:55], v[50:51], v[54:55]
	v_pk_fma_f32 v[50:51], v[56:57], v[174:175], v[84:85] op_sel_hi:[1,0,1]
	s_nop 0
	v_mul_f32_e32 v56, 0xbfb8aa3b, v50
	v_mul_f32_e32 v57, 0xbfb8aa3b, v51
	v_exp_f32_e32 v56, v56
	v_exp_f32_e32 v57, v57
	v_add_f32_e32 v56, 1.0, v56
	v_add_f32_e32 v57, 1.0, v57
	v_rcp_f32_e32 v56, v56
	v_rcp_f32_e32 v57, v57
	s_nop 0
	v_pk_mul_f32 v[50:51], v[50:51], v[56:57]
	s_nop 0
	v_pk_mul_f32 v[56:57], v[52:53], v[50:51]
	v_cvt_pk_bf16_f32 v52, v54, v55
	v_lshrrev_b32_e32 v54, 8, v181
	v_mad_i32_i24 v54, v54, 44, v161
	v_ashrrev_i32_e32 v55, 31, v54
	v_cvt_pk_bf16_f32 v53, v56, v57
	v_lshlrev_b64 v[54:55], 15, v[54:55]
	v_lshlrev_b32_e32 v56, 7, v181
	v_lshl_add_u64 v[54:55], s[14:15], 0, v[54:55]
	v_and_b32_e32 v56, 0x7f80, v56
	v_mov_b32_e32 v57, v0
	v_lshl_add_u64 v[54:55], v[54:55], 0, v[56:57]
	v_cvt_pk_bf16_f32 v50, v58, v59
	v_cvt_pk_bf16_f32 v51, v60, v61
	v_lshl_add_u64 v[54:55], v[54:55], 0, v[130:131]
	global_store_dwordx4 v[54:55], v[50:53], off nt
	v_pk_fma_f32 v[46:47], v[46:47], v[172:173], v[98:99] op_sel_hi:[1,0,1]
	v_pk_fma_f32 v[42:43], v[42:43], v[172:173], v[102:103] op_sel_hi:[1,0,1]
	v_mul_f32_e32 v50, 0xbfb8aa3b, v46
	v_mul_f32_e32 v51, 0xbfb8aa3b, v47
	v_exp_f32_e32 v50, v50
	v_exp_f32_e32 v51, v51
	v_pk_fma_f32 v[44:45], v[44:45], v[172:173], v[104:105] op_sel_hi:[1,0,1]
	v_pk_fma_f32 v[38:39], v[38:39], v[172:173], v[82:83] op_sel_hi:[1,0,1]
	v_add_f32_e32 v50, 1.0, v50
	v_add_f32_e32 v51, 1.0, v51
	v_rcp_f32_e32 v50, v50
	v_rcp_f32_e32 v51, v51
	v_pk_fma_f32 v[34:35], v[34:35], v[172:173], v[86:87] op_sel_hi:[1,0,1]
	v_pk_fma_f32 v[36:37], v[36:37], v[172:173], v[88:89] op_sel_hi:[1,0,1]
	v_pk_mul_f32 v[46:47], v[46:47], v[50:51]
	s_nop 0
	v_pk_mul_f32 v[42:43], v[42:43], v[46:47]
	v_pk_fma_f32 v[46:47], v[48:49], v[172:173], v[100:101] op_sel_hi:[1,0,1]
	s_nop 0
	v_mul_f32_e32 v48, 0xbfb8aa3b, v46
	v_mul_f32_e32 v49, 0xbfb8aa3b, v47
	v_exp_f32_e32 v48, v48
	v_exp_f32_e32 v49, v49
	v_add_f32_e32 v48, 1.0, v48
	v_add_f32_e32 v49, 1.0, v49
	v_rcp_f32_e32 v48, v48
	v_rcp_f32_e32 v49, v49
	s_nop 0
	v_pk_mul_f32 v[46:47], v[46:47], v[48:49]
	s_nop 0
	v_pk_mul_f32 v[44:45], v[44:45], v[46:47]
	v_mul_f32_e32 v46, 0xbfb8aa3b, v38
	v_mul_f32_e32 v47, 0xbfb8aa3b, v39
	v_exp_f32_e32 v46, v46
	v_exp_f32_e32 v47, v47
	v_add_f32_e32 v46, 1.0, v46
	v_add_f32_e32 v47, 1.0, v47
	v_rcp_f32_e32 v46, v46
	v_rcp_f32_e32 v47, v47
	s_nop 0
	v_pk_mul_f32 v[38:39], v[38:39], v[46:47]
	s_nop 0
	v_pk_mul_f32 v[38:39], v[34:35], v[38:39]
	v_pk_fma_f32 v[34:35], v[40:41], v[172:173], v[84:85] op_sel_hi:[1,0,1]
	s_nop 0
	v_mul_f32_e32 v40, 0xbfb8aa3b, v34
	v_mul_f32_e32 v41, 0xbfb8aa3b, v35
	v_exp_f32_e32 v40, v40
	v_exp_f32_e32 v41, v41
	v_add_f32_e32 v40, 1.0, v40
	v_add_f32_e32 v41, 1.0, v41
	v_rcp_f32_e32 v40, v40
	v_rcp_f32_e32 v41, v41
	s_nop 0
	v_pk_mul_f32 v[34:35], v[34:35], v[40:41]
	s_nop 0
	v_pk_mul_f32 v[40:41], v[36:37], v[34:35]
	v_cvt_pk_bf16_f32 v36, v38, v39
	v_lshrrev_b32_e32 v38, 8, v179
	v_mad_i32_i24 v38, v38, 44, v161
	v_ashrrev_i32_e32 v39, 31, v38
	v_cvt_pk_bf16_f32 v37, v40, v41
	v_lshlrev_b64 v[38:39], 15, v[38:39]
	v_lshlrev_b32_e32 v40, 7, v179
	v_lshl_add_u64 v[38:39], s[14:15], 0, v[38:39]
	v_and_b32_e32 v40, 0x7f80, v40
	v_mov_b32_e32 v41, v0
	v_lshl_add_u64 v[38:39], v[38:39], 0, v[40:41]
	v_cvt_pk_bf16_f32 v34, v42, v43
	v_cvt_pk_bf16_f32 v35, v44, v45
	v_lshl_add_u64 v[38:39], v[38:39], 0, v[130:131]
	global_store_dwordx4 v[38:39], v[34:37], off nt
	v_pk_fma_f32 v[30:31], v[30:31], v[158:159], v[98:99] op_sel_hi:[1,0,1]
	v_pk_fma_f32 v[26:27], v[26:27], v[158:159], v[102:103] op_sel_hi:[1,0,1]
	v_mul_f32_e32 v34, 0xbfb8aa3b, v30
	v_mul_f32_e32 v35, 0xbfb8aa3b, v31
	v_exp_f32_e32 v34, v34
	v_exp_f32_e32 v35, v35
	v_pk_fma_f32 v[28:29], v[28:29], v[158:159], v[104:105] op_sel_hi:[1,0,1]
	v_pk_fma_f32 v[22:23], v[22:23], v[158:159], v[82:83] op_sel_hi:[1,0,1]
	v_add_f32_e32 v34, 1.0, v34
	v_add_f32_e32 v35, 1.0, v35
	v_rcp_f32_e32 v34, v34
	v_rcp_f32_e32 v35, v35
	v_pk_fma_f32 v[18:19], v[18:19], v[158:159], v[86:87] op_sel_hi:[1,0,1]
	v_pk_fma_f32 v[20:21], v[20:21], v[158:159], v[88:89] op_sel_hi:[1,0,1]
	v_pk_mul_f32 v[30:31], v[30:31], v[34:35]
	s_nop 0
	v_pk_mul_f32 v[26:27], v[26:27], v[30:31]
	v_pk_fma_f32 v[30:31], v[32:33], v[158:159], v[100:101] op_sel_hi:[1,0,1]
	s_nop 0
	v_mul_f32_e32 v32, 0xbfb8aa3b, v30
	v_mul_f32_e32 v33, 0xbfb8aa3b, v31
	v_exp_f32_e32 v32, v32
	v_exp_f32_e32 v33, v33
	v_add_f32_e32 v32, 1.0, v32
	v_add_f32_e32 v33, 1.0, v33
	v_rcp_f32_e32 v32, v32
	v_rcp_f32_e32 v33, v33
	s_nop 0
	v_pk_mul_f32 v[30:31], v[30:31], v[32:33]
	s_nop 0
	v_pk_mul_f32 v[28:29], v[28:29], v[30:31]
	v_mul_f32_e32 v30, 0xbfb8aa3b, v22
	v_mul_f32_e32 v31, 0xbfb8aa3b, v23
	v_exp_f32_e32 v30, v30
	v_exp_f32_e32 v31, v31
	v_add_f32_e32 v30, 1.0, v30
	v_add_f32_e32 v31, 1.0, v31
	v_rcp_f32_e32 v30, v30
	v_rcp_f32_e32 v31, v31
	s_nop 0
	v_pk_mul_f32 v[22:23], v[22:23], v[30:31]
	s_nop 0
	v_pk_mul_f32 v[22:23], v[18:19], v[22:23]
	v_pk_fma_f32 v[18:19], v[24:25], v[158:159], v[84:85] op_sel_hi:[1,0,1]
	s_nop 0
	v_mul_f32_e32 v24, 0xbfb8aa3b, v18
	v_mul_f32_e32 v25, 0xbfb8aa3b, v19
	v_exp_f32_e32 v24, v24
	v_exp_f32_e32 v25, v25
	v_add_f32_e32 v24, 1.0, v24
	v_add_f32_e32 v25, 1.0, v25
	v_rcp_f32_e32 v24, v24
	v_rcp_f32_e32 v25, v25
	s_nop 0
	v_pk_mul_f32 v[18:19], v[18:19], v[24:25]
	s_nop 0
	v_pk_mul_f32 v[24:25], v[20:21], v[18:19]
	v_cvt_pk_bf16_f32 v20, v22, v23
	v_lshrrev_b32_e32 v22, 8, v177
	v_mad_i32_i24 v22, v22, 44, v161
	v_ashrrev_i32_e32 v23, 31, v22
	v_cvt_pk_bf16_f32 v21, v24, v25
	v_lshlrev_b64 v[22:23], 15, v[22:23]
	v_lshlrev_b32_e32 v24, 7, v177
	v_lshl_add_u64 v[22:23], s[14:15], 0, v[22:23]
	v_and_b32_e32 v24, 0x7f80, v24
	v_mov_b32_e32 v25, v0
	v_lshl_add_u64 v[22:23], v[22:23], 0, v[24:25]
	v_cvt_pk_bf16_f32 v18, v26, v27
	v_cvt_pk_bf16_f32 v19, v28, v29
	v_lshl_add_u64 v[22:23], v[22:23], 0, v[130:131]
	global_store_dwordx4 v[22:23], v[18:21], off nt
	v_pk_fma_f32 v[14:15], v[14:15], v[160:161], v[98:99] op_sel_hi:[1,0,1]
	v_pk_fma_f32 v[10:11], v[10:11], v[160:161], v[102:103] op_sel_hi:[1,0,1]
	v_mul_f32_e32 v18, 0xbfb8aa3b, v14
	v_mul_f32_e32 v19, 0xbfb8aa3b, v15
	v_exp_f32_e32 v18, v18
	v_exp_f32_e32 v19, v19
	v_pk_fma_f32 v[12:13], v[12:13], v[160:161], v[104:105] op_sel_hi:[1,0,1]
	v_pk_fma_f32 v[6:7], v[6:7], v[160:161], v[82:83] op_sel_hi:[1,0,1]
	v_add_f32_e32 v18, 1.0, v18
	v_add_f32_e32 v19, 1.0, v19
	v_rcp_f32_e32 v18, v18
	v_rcp_f32_e32 v19, v19
	v_pk_fma_f32 v[2:3], v[2:3], v[160:161], v[86:87] op_sel_hi:[1,0,1]
	v_pk_fma_f32 v[4:5], v[4:5], v[160:161], v[88:89] op_sel_hi:[1,0,1]
	s_and_b64 vcc, exec, s[36:37]
	v_pk_mul_f32 v[14:15], v[14:15], v[18:19]
	s_mov_b32 s42, s4
	v_pk_mul_f32 v[10:11], v[10:11], v[14:15]
	v_pk_fma_f32 v[14:15], v[16:17], v[160:161], v[100:101] op_sel_hi:[1,0,1]
	s_mov_b32 s12, s6
	v_mul_f32_e32 v16, 0xbfb8aa3b, v14
	v_mul_f32_e32 v17, 0xbfb8aa3b, v15
	v_exp_f32_e32 v16, v16
	v_exp_f32_e32 v17, v17
	s_mov_b64 s[16:17], s[10:11]
	v_add_f32_e32 v16, 1.0, v16
	v_add_f32_e32 v17, 1.0, v17
	v_rcp_f32_e32 v16, v16
	v_rcp_f32_e32 v17, v17
	s_nop 0
	v_pk_mul_f32 v[14:15], v[14:15], v[16:17]
	s_nop 0
	v_pk_mul_f32 v[12:13], v[12:13], v[14:15]
	v_mul_f32_e32 v14, 0xbfb8aa3b, v6
	v_mul_f32_e32 v15, 0xbfb8aa3b, v7
	v_exp_f32_e32 v14, v14
	v_exp_f32_e32 v15, v15
	v_add_f32_e32 v14, 1.0, v14
	v_add_f32_e32 v15, 1.0, v15
	v_rcp_f32_e32 v14, v14
	v_rcp_f32_e32 v15, v15
	s_nop 0
	v_pk_mul_f32 v[6:7], v[6:7], v[14:15]
	s_nop 0
	v_pk_mul_f32 v[6:7], v[2:3], v[6:7]
	v_pk_fma_f32 v[2:3], v[8:9], v[160:161], v[84:85] op_sel_hi:[1,0,1]
	s_nop 0
	v_mul_f32_e32 v8, 0xbfb8aa3b, v2
	v_mul_f32_e32 v9, 0xbfb8aa3b, v3
	v_exp_f32_e32 v8, v8
	v_exp_f32_e32 v9, v9
	v_add_f32_e32 v8, 1.0, v8
	v_add_f32_e32 v9, 1.0, v9
	v_rcp_f32_e32 v8, v8
	v_rcp_f32_e32 v9, v9
	s_nop 0
	v_pk_mul_f32 v[2:3], v[2:3], v[8:9]
	s_nop 0
	v_pk_mul_f32 v[8:9], v[4:5], v[2:3]
	v_cvt_pk_bf16_f32 v4, v6, v7
	v_lshrrev_b32_e32 v6, 8, v175
	v_mad_i32_i24 v6, v6, 44, v161
	v_ashrrev_i32_e32 v7, 31, v6
	v_cvt_pk_bf16_f32 v5, v8, v9
	v_lshlrev_b64 v[6:7], 15, v[6:7]
	v_lshlrev_b32_e32 v8, 7, v175
	v_lshl_add_u64 v[6:7], s[14:15], 0, v[6:7]
	v_and_b32_e32 v8, 0x7f80, v8
	v_mov_b32_e32 v9, v0
	v_lshl_add_u64 v[6:7], v[6:7], 0, v[8:9]
	v_cvt_pk_bf16_f32 v2, v10, v11
	v_cvt_pk_bf16_f32 v3, v12, v13
	v_lshl_add_u64 v[6:7], v[6:7], 0, v[130:131]
	s_mov_b64 s[14:15], s[8:9]
	global_store_dwordx4 v[6:7], v[2:5], off nt
	s_cbranch_vccnz .LBB0_564

.LBB0_619:
	s_lshl_b32 s5, s12, 8
	v_mov_b32_e32 v82, v159
	v_mov_b32_e32 v83, v1
	s_add_i32 s5, s5, s31
	s_nop 0
	v_add_u32_e32 v182, s5, v82
	s_lshl_b32 s5, s42, 7
	s_or_b32 s5, s5, s34
	v_lshl_add_u32 v186, v83, 3, s5
	s_ashr_i32 s5, s12, 5
	s_mul_hi_i32 s7, s5, 0x5800
	s_mulk_i32 s5, 0x5800
	s_add_u32 s14, s28, s5
	s_addc_u32 s15, s29, s7
	v_ashrrev_i32_e32 v187, 31, v186
	v_lshl_add_u64 v[86:87], v[186:187], 2, s[14:15]
	s_mov_b64 s[14:15], 0x2c00
	s_movk_i32 s5, 0x2000
	global_load_dwordx4 v[82:85], v[86:87], off offset:16
	global_load_dwordx4 v[98:101], v[86:87], off
	v_lshl_add_u64 v[88:89], v[86:87], 0, s[14:15]
	v_add_co_u32_e32 v86, vcc, s5, v86
	v_ashrrev_i32_e32 v183, 31, v182
	s_nop 0
	v_addc_co_u32_e32 v87, vcc, 0, v87, vcc
	v_lshl_add_u64 v[160:161], v[182:183], 2, s[0:1]
	global_load_dwordx4 v[102:105], v[86:87], off offset:3072
	s_nop 0
	global_load_dwordx4 v[86:89], v[88:89], off offset:16
	v_add_u32_e32 v187, 16, v182
	global_load_dword v184, v[160:161], off
	global_load_dword v180, v[160:161], off offset:64
	global_load_dword v178, v[160:161], off offset:128
	global_load_dword v176, v[160:161], off offset:192
	global_load_dword v174, v[160:161], off offset:512
	global_load_dword v172, v[160:161], off offset:576
	global_load_dword v175, v[160:161], off offset:640
	global_load_dword v160, v[160:161], off offset:704
	v_add_u32_e32 v185, 32, v182
	v_add_u32_e32 v183, 48, v182
	v_add_u32_e32 v181, 0x80, v182
	v_add_u32_e32 v179, 0x90, v182
	v_add_u32_e32 v177, 0xa0, v182
	s_waitcnt vmcnt(0)
	v_fmamk_f32 v158, v184, 0x3a800000, v223
	v_cmp_gt_f32_e32 vcc, s95, v158
	v_mul_f32_e32 v168, 0x4b800000, v158
	s_nop 0
	v_cndmask_b32_e32 v158, v158, v168, vcc
	v_rsq_f32_e32 v158, v158
	s_nop 0
	v_mul_f32_e32 v168, 0x45800000, v158
	v_cndmask_b32_e32 v184, v158, v168, vcc
	v_fmamk_f32 v158, v180, 0x3a800000, v223
	v_cmp_gt_f32_e32 vcc, s95, v158
	v_mul_f32_e32 v168, 0x4b800000, v158
	s_nop 0
	v_cndmask_b32_e32 v158, v158, v168, vcc
	v_rsq_f32_e32 v158, v158
	s_nop 0
	v_mul_f32_e32 v168, 0x45800000, v158
	v_cndmask_b32_e32 v180, v158, v168, vcc
	v_fmamk_f32 v158, v178, 0x3a800000, v223
	v_cmp_gt_f32_e32 vcc, s95, v158
	v_mul_f32_e32 v168, 0x4b800000, v158
	s_nop 0
	v_cndmask_b32_e32 v158, v158, v168, vcc
	v_rsq_f32_e32 v158, v158
	s_nop 0
	v_mul_f32_e32 v168, 0x45800000, v158
	v_cndmask_b32_e32 v178, v158, v168, vcc
	v_fmamk_f32 v158, v176, 0x3a800000, v223
	v_cmp_gt_f32_e32 vcc, s95, v158
	v_mul_f32_e32 v168, 0x4b800000, v158
	s_nop 0
	v_cndmask_b32_e32 v158, v158, v168, vcc
	v_rsq_f32_e32 v158, v158
	s_nop 0
	v_mul_f32_e32 v168, 0x45800000, v158
	v_cndmask_b32_e32 v176, v158, v168, vcc
	v_fmamk_f32 v158, v174, 0x3a800000, v223
	v_cmp_gt_f32_e32 vcc, s95, v158
	v_mul_f32_e32 v168, 0x4b800000, v158
	s_nop 0
	v_cndmask_b32_e32 v158, v158, v168, vcc
	v_rsq_f32_e32 v158, v158
	s_nop 0
	v_mul_f32_e32 v168, 0x45800000, v158
	v_cndmask_b32_e32 v174, v158, v168, vcc
	v_fmamk_f32 v158, v172, 0x3a800000, v223
	v_cmp_gt_f32_e32 vcc, s95, v158
	v_mul_f32_e32 v168, 0x4b800000, v158
	s_nop 0
	v_cndmask_b32_e32 v158, v158, v168, vcc
	v_rsq_f32_e32 v158, v158
	s_nop 0
	v_mul_f32_e32 v168, 0x45800000, v158
	v_cndmask_b32_e32 v172, v158, v168, vcc
	v_fmamk_f32 v158, v175, 0x3a800000, v223
	v_add_u32_e32 v175, 0xb0, v182
	v_cmp_gt_f32_e32 vcc, s95, v158
	v_mul_f32_e32 v168, 0x4b800000, v158
	v_fmamk_f32 v160, v160, 0x3a800000, v223
	v_cndmask_b32_e32 v158, v158, v168, vcc
	v_rsq_f32_e32 v158, v158
	v_mul_f32_e32 v161, 0x4b800000, v160
	v_mul_f32_e32 v168, 0x45800000, v158
	v_cndmask_b32_e32 v158, v158, v168, vcc
	v_cmp_gt_f32_e32 vcc, s95, v160
	v_and_b32_e32 v168, 56, v186
	s_nop 0
	v_cndmask_b32_e32 v160, v160, v161, vcc
	v_rsq_f32_e32 v160, v160
	s_nop 0
	v_mul_f32_e32 v161, 0x45800000, v160
	v_cndmask_b32_e32 v160, v160, v161, vcc
	v_ashrrev_i32_e32 v161, 6, v186
	v_pk_fma_f32 v[138:139], v[138:139], v[184:185], v[98:99] op_sel_hi:[1,0,1]
	v_pk_fma_f32 v[142:143], v[142:143], v[184:185], v[102:103] op_sel_hi:[1,0,1]
	v_mul_f32_e32 v169, 0xbfb8aa3b, v138
	v_exp_f32_e32 v169, v169
	v_pk_fma_f32 v[140:141], v[140:141], v[184:185], v[100:101] op_sel_hi:[1,0,1]
	v_pk_fma_f32 v[134:135], v[134:135], v[184:185], v[82:83] op_sel_hi:[1,0,1]
	v_pk_fma_f32 v[130:131], v[130:131], v[184:185], v[86:87] op_sel_hi:[1,0,1]
	v_add_f32_e32 v169, 1.0, v169
	v_rcp_f32_e32 v188, v169
	v_mul_f32_e32 v169, 0xbfb8aa3b, v139
	v_exp_f32_e32 v169, v169
	v_pk_fma_f32 v[132:133], v[132:133], v[184:185], v[88:89] op_sel_hi:[1,0,1]
	v_readlane_b32 s14, v254, 27
	v_readlane_b32 s15, v254, 28
	v_add_f32_e32 v169, 1.0, v169
	v_rcp_f32_e32 v189, v169
	s_nop 0
	v_pk_mul_f32 v[138:139], v[138:139], v[188:189]
	s_nop 0
	v_pk_mul_f32 v[138:139], v[142:143], v[138:139]
	v_pk_fma_f32 v[142:143], v[144:145], v[184:185], v[104:105] op_sel_hi:[1,0,1]
	v_mul_f32_e32 v144, 0xbfb8aa3b, v140
	v_mul_f32_e32 v145, 0xbfb8aa3b, v141
	v_exp_f32_e32 v144, v144
	v_exp_f32_e32 v145, v145
	v_add_f32_e32 v144, 1.0, v144
	v_add_f32_e32 v145, 1.0, v145
	v_rcp_f32_e32 v144, v144
	v_rcp_f32_e32 v145, v145
	s_nop 0
	v_pk_mul_f32 v[140:141], v[140:141], v[144:145]
	s_nop 0
	v_pk_mul_f32 v[140:141], v[142:143], v[140:141]
	v_mul_f32_e32 v142, 0xbfb8aa3b, v134
	v_mul_f32_e32 v143, 0xbfb8aa3b, v135
	v_exp_f32_e32 v142, v142
	v_exp_f32_e32 v143, v143
	v_add_f32_e32 v142, 1.0, v142
	v_add_f32_e32 v143, 1.0, v143
	v_rcp_f32_e32 v142, v142
	v_rcp_f32_e32 v143, v143
	s_nop 0
	v_pk_mul_f32 v[134:135], v[134:135], v[142:143]
	s_nop 0
	v_pk_mul_f32 v[130:131], v[130:131], v[134:135]
	v_pk_fma_f32 v[134:135], v[136:137], v[184:185], v[84:85] op_sel_hi:[1,0,1]
	s_nop 0
	v_mul_f32_e32 v136, 0xbfb8aa3b, v134
	v_mul_f32_e32 v137, 0xbfb8aa3b, v135
	v_exp_f32_e32 v136, v136
	v_exp_f32_e32 v137, v137
	v_add_f32_e32 v136, 1.0, v136
	v_add_f32_e32 v137, 1.0, v137
	v_rcp_f32_e32 v136, v136
	v_rcp_f32_e32 v137, v137
	s_nop 0
	v_pk_mul_f32 v[134:135], v[134:135], v[136:137]
	s_nop 0
	v_pk_mul_f32 v[136:137], v[132:133], v[134:135]
	v_cvt_pk_bf16_f32 v134, v130, v131
	v_lshrrev_b32_e32 v130, 8, v182
	v_mad_i32_i24 v130, v130, 44, v161
	v_ashrrev_i32_e32 v131, 31, v130
	v_cvt_pk_bf16_f32 v135, v136, v137
	v_lshlrev_b64 v[130:131], 15, v[130:131]
	v_lshlrev_b32_e32 v136, 7, v182
	v_lshl_add_u64 v[130:131], s[14:15], 0, v[130:131]
	v_and_b32_e32 v136, 0x7f80, v136
	v_mov_b32_e32 v137, v0
	v_lshl_add_u64 v[136:137], v[130:131], 0, v[136:137]
	v_lshlrev_b32_e32 v130, 1, v168
	v_mov_b32_e32 v131, v0
	v_cvt_pk_bf16_f32 v132, v138, v139
	v_cvt_pk_bf16_f32 v133, v140, v141
	v_lshl_add_u64 v[136:137], v[136:137], 0, v[130:131]
	global_store_dwordx4 v[136:137], v[132:135], off nt
	v_pk_fma_f32 v[126:127], v[126:127], v[180:181], v[98:99] op_sel_hi:[1,0,1]
	v_pk_fma_f32 v[122:123], v[122:123], v[180:181], v[102:103] op_sel_hi:[1,0,1]
	v_mul_f32_e32 v132, 0xbfb8aa3b, v126
	v_mul_f32_e32 v133, 0xbfb8aa3b, v127
	v_exp_f32_e32 v132, v132
	v_exp_f32_e32 v133, v133
	v_pk_fma_f32 v[124:125], v[124:125], v[180:181], v[104:105] op_sel_hi:[1,0,1]
	v_pk_fma_f32 v[118:119], v[118:119], v[180:181], v[82:83] op_sel_hi:[1,0,1]
	v_add_f32_e32 v132, 1.0, v132
	v_add_f32_e32 v133, 1.0, v133
	v_rcp_f32_e32 v132, v132
	v_rcp_f32_e32 v133, v133
	v_pk_fma_f32 v[114:115], v[114:115], v[180:181], v[86:87] op_sel_hi:[1,0,1]
	v_pk_fma_f32 v[116:117], v[116:117], v[180:181], v[88:89] op_sel_hi:[1,0,1]
	v_pk_mul_f32 v[126:127], v[126:127], v[132:133]
	s_nop 0
	v_pk_mul_f32 v[122:123], v[122:123], v[126:127]
	v_pk_fma_f32 v[126:127], v[128:129], v[180:181], v[100:101] op_sel_hi:[1,0,1]
	s_nop 0
	v_mul_f32_e32 v128, 0xbfb8aa3b, v126
	v_mul_f32_e32 v129, 0xbfb8aa3b, v127
	v_exp_f32_e32 v128, v128
	v_exp_f32_e32 v129, v129
	v_add_f32_e32 v128, 1.0, v128
	v_add_f32_e32 v129, 1.0, v129
	v_rcp_f32_e32 v128, v128
	v_rcp_f32_e32 v129, v129
	s_nop 0
	v_pk_mul_f32 v[126:127], v[126:127], v[128:129]
	s_nop 0
	v_pk_mul_f32 v[124:125], v[124:125], v[126:127]
	v_mul_f32_e32 v126, 0xbfb8aa3b, v118
	v_mul_f32_e32 v127, 0xbfb8aa3b, v119
	v_exp_f32_e32 v126, v126
	v_exp_f32_e32 v127, v127
	v_add_f32_e32 v126, 1.0, v126
	v_add_f32_e32 v127, 1.0, v127
	v_rcp_f32_e32 v126, v126
	v_rcp_f32_e32 v127, v127
	s_nop 0
	v_pk_mul_f32 v[118:119], v[118:119], v[126:127]
	s_nop 0
	v_pk_mul_f32 v[118:119], v[114:115], v[118:119]
	v_pk_fma_f32 v[114:115], v[120:121], v[180:181], v[84:85] op_sel_hi:[1,0,1]
	s_nop 0
	v_mul_f32_e32 v120, 0xbfb8aa3b, v114
	v_mul_f32_e32 v121, 0xbfb8aa3b, v115
	v_exp_f32_e32 v120, v120
	v_exp_f32_e32 v121, v121
	v_add_f32_e32 v120, 1.0, v120
	v_add_f32_e32 v121, 1.0, v121
	v_rcp_f32_e32 v120, v120
	v_rcp_f32_e32 v121, v121
	s_nop 0
	v_pk_mul_f32 v[114:115], v[114:115], v[120:121]
	s_nop 0
	v_pk_mul_f32 v[120:121], v[116:117], v[114:115]
	v_cvt_pk_bf16_f32 v116, v118, v119
	v_lshrrev_b32_e32 v118, 8, v187
	v_mad_i32_i24 v118, v118, 44, v161
	v_ashrrev_i32_e32 v119, 31, v118
	v_cvt_pk_bf16_f32 v117, v120, v121
	v_lshlrev_b64 v[118:119], 15, v[118:119]
	v_lshlrev_b32_e32 v120, 7, v187
	v_lshl_add_u64 v[118:119], s[14:15], 0, v[118:119]
	v_and_b32_e32 v120, 0x7f80, v120
	v_mov_b32_e32 v121, v0
	v_lshl_add_u64 v[118:119], v[118:119], 0, v[120:121]
	v_cvt_pk_bf16_f32 v114, v122, v123
	v_cvt_pk_bf16_f32 v115, v124, v125
	v_lshl_add_u64 v[118:119], v[118:119], 0, v[130:131]
	global_store_dwordx4 v[118:119], v[114:117], off nt
	v_pk_fma_f32 v[110:111], v[110:111], v[178:179], v[98:99] op_sel_hi:[1,0,1]
	v_pk_fma_f32 v[106:107], v[106:107], v[178:179], v[102:103] op_sel_hi:[1,0,1]
	v_mul_f32_e32 v114, 0xbfb8aa3b, v110
	v_mul_f32_e32 v115, 0xbfb8aa3b, v111
	v_exp_f32_e32 v114, v114
	v_exp_f32_e32 v115, v115
	v_pk_fma_f32 v[108:109], v[108:109], v[178:179], v[104:105] op_sel_hi:[1,0,1]
	v_pk_fma_f32 v[94:95], v[94:95], v[178:179], v[82:83] op_sel_hi:[1,0,1]
	v_add_f32_e32 v114, 1.0, v114
	v_add_f32_e32 v115, 1.0, v115
	v_rcp_f32_e32 v114, v114
	v_rcp_f32_e32 v115, v115
	v_pk_fma_f32 v[90:91], v[90:91], v[178:179], v[86:87] op_sel_hi:[1,0,1]
	v_pk_fma_f32 v[92:93], v[92:93], v[178:179], v[88:89] op_sel_hi:[1,0,1]
	v_pk_mul_f32 v[110:111], v[110:111], v[114:115]
	s_nop 0
	v_pk_mul_f32 v[106:107], v[106:107], v[110:111]
	v_pk_fma_f32 v[110:111], v[112:113], v[178:179], v[100:101] op_sel_hi:[1,0,1]
	s_nop 0
	v_mul_f32_e32 v112, 0xbfb8aa3b, v110
	v_mul_f32_e32 v113, 0xbfb8aa3b, v111
	v_exp_f32_e32 v112, v112
	v_exp_f32_e32 v113, v113
	v_add_f32_e32 v112, 1.0, v112
	v_add_f32_e32 v113, 1.0, v113
	v_rcp_f32_e32 v112, v112
	v_rcp_f32_e32 v113, v113
	s_nop 0
	v_pk_mul_f32 v[110:111], v[110:111], v[112:113]
	s_nop 0
	v_pk_mul_f32 v[108:109], v[108:109], v[110:111]
	v_mul_f32_e32 v110, 0xbfb8aa3b, v94
	v_mul_f32_e32 v111, 0xbfb8aa3b, v95
	v_exp_f32_e32 v110, v110
	v_exp_f32_e32 v111, v111
	v_add_f32_e32 v110, 1.0, v110
	v_add_f32_e32 v111, 1.0, v111
	v_rcp_f32_e32 v110, v110
	v_rcp_f32_e32 v111, v111
	s_nop 0
	v_pk_mul_f32 v[94:95], v[94:95], v[110:111]
	s_nop 0
	v_pk_mul_f32 v[94:95], v[90:91], v[94:95]
	v_pk_fma_f32 v[90:91], v[96:97], v[178:179], v[84:85] op_sel_hi:[1,0,1]
	s_nop 0
	v_mul_f32_e32 v96, 0xbfb8aa3b, v90
	v_mul_f32_e32 v97, 0xbfb8aa3b, v91
	v_exp_f32_e32 v96, v96
	v_exp_f32_e32 v97, v97
	v_add_f32_e32 v96, 1.0, v96
	v_add_f32_e32 v97, 1.0, v97
	v_rcp_f32_e32 v96, v96
	v_rcp_f32_e32 v97, v97
	s_nop 0
	v_pk_mul_f32 v[90:91], v[90:91], v[96:97]
	s_nop 0
	v_pk_mul_f32 v[96:97], v[92:93], v[90:91]
	v_cvt_pk_bf16_f32 v92, v94, v95
	v_lshrrev_b32_e32 v94, 8, v185
	v_mad_i32_i24 v94, v94, 44, v161
	v_ashrrev_i32_e32 v95, 31, v94
	v_cvt_pk_bf16_f32 v93, v96, v97
	v_lshlrev_b64 v[94:95], 15, v[94:95]
	v_lshlrev_b32_e32 v96, 7, v185
	v_lshl_add_u64 v[94:95], s[14:15], 0, v[94:95]
	v_and_b32_e32 v96, 0x7f80, v96
	v_mov_b32_e32 v97, v0
	v_lshl_add_u64 v[94:95], v[94:95], 0, v[96:97]
	v_cvt_pk_bf16_f32 v90, v106, v107
	v_cvt_pk_bf16_f32 v91, v108, v109
	v_lshl_add_u64 v[94:95], v[94:95], 0, v[130:131]
	global_store_dwordx4 v[94:95], v[90:93], off nt
	v_pk_fma_f32 v[78:79], v[78:79], v[176:177], v[98:99] op_sel_hi:[1,0,1]
	v_pk_fma_f32 v[74:75], v[74:75], v[176:177], v[102:103] op_sel_hi:[1,0,1]
	v_mul_f32_e32 v90, 0xbfb8aa3b, v78
	v_mul_f32_e32 v91, 0xbfb8aa3b, v79
	v_exp_f32_e32 v90, v90
	v_exp_f32_e32 v91, v91
	v_pk_fma_f32 v[76:77], v[76:77], v[176:177], v[104:105] op_sel_hi:[1,0,1]
	v_pk_fma_f32 v[70:71], v[70:71], v[176:177], v[82:83] op_sel_hi:[1,0,1]
	v_add_f32_e32 v90, 1.0, v90
	v_add_f32_e32 v91, 1.0, v91
	v_rcp_f32_e32 v90, v90
	v_rcp_f32_e32 v91, v91
	v_pk_fma_f32 v[66:67], v[66:67], v[176:177], v[86:87] op_sel_hi:[1,0,1]
	v_pk_fma_f32 v[68:69], v[68:69], v[176:177], v[88:89] op_sel_hi:[1,0,1]
	v_pk_mul_f32 v[78:79], v[78:79], v[90:91]
	s_nop 0
	v_pk_mul_f32 v[74:75], v[74:75], v[78:79]
	v_pk_fma_f32 v[78:79], v[80:81], v[176:177], v[100:101] op_sel_hi:[1,0,1]
	s_nop 0
	v_mul_f32_e32 v80, 0xbfb8aa3b, v78
	v_mul_f32_e32 v81, 0xbfb8aa3b, v79
	v_exp_f32_e32 v80, v80
	v_exp_f32_e32 v81, v81
	v_add_f32_e32 v80, 1.0, v80
	v_add_f32_e32 v81, 1.0, v81
	v_rcp_f32_e32 v80, v80
	v_rcp_f32_e32 v81, v81
	s_nop 0
	v_pk_mul_f32 v[78:79], v[78:79], v[80:81]
	s_nop 0
	v_pk_mul_f32 v[76:77], v[76:77], v[78:79]
	v_mul_f32_e32 v78, 0xbfb8aa3b, v70
	v_mul_f32_e32 v79, 0xbfb8aa3b, v71
	v_exp_f32_e32 v78, v78
	v_exp_f32_e32 v79, v79
	v_add_f32_e32 v78, 1.0, v78
	v_add_f32_e32 v79, 1.0, v79
	v_rcp_f32_e32 v78, v78
	v_rcp_f32_e32 v79, v79
	s_nop 0
	v_pk_mul_f32 v[70:71], v[70:71], v[78:79]
	s_nop 0
	v_pk_mul_f32 v[70:71], v[66:67], v[70:71]
	v_pk_fma_f32 v[66:67], v[72:73], v[176:177], v[84:85] op_sel_hi:[1,0,1]
	s_nop 0
	v_mul_f32_e32 v72, 0xbfb8aa3b, v66
	v_mul_f32_e32 v73, 0xbfb8aa3b, v67
	v_exp_f32_e32 v72, v72
	v_exp_f32_e32 v73, v73
	v_add_f32_e32 v72, 1.0, v72
	v_add_f32_e32 v73, 1.0, v73
	v_rcp_f32_e32 v72, v72
	v_rcp_f32_e32 v73, v73
	s_nop 0
	v_pk_mul_f32 v[66:67], v[66:67], v[72:73]
	s_nop 0
	v_pk_mul_f32 v[72:73], v[68:69], v[66:67]
	v_cvt_pk_bf16_f32 v68, v70, v71
	v_lshrrev_b32_e32 v70, 8, v183
	v_mad_i32_i24 v70, v70, 44, v161
	v_ashrrev_i32_e32 v71, 31, v70
	v_cvt_pk_bf16_f32 v69, v72, v73
	v_lshlrev_b64 v[70:71], 15, v[70:71]
	v_lshlrev_b32_e32 v72, 7, v183
	v_lshl_add_u64 v[70:71], s[14:15], 0, v[70:71]
	v_and_b32_e32 v72, 0x7f80, v72
	v_mov_b32_e32 v73, v0
	v_lshl_add_u64 v[70:71], v[70:71], 0, v[72:73]
	v_cvt_pk_bf16_f32 v66, v74, v75
	v_cvt_pk_bf16_f32 v67, v76, v77
	v_lshl_add_u64 v[70:71], v[70:71], 0, v[130:131]
	global_store_dwordx4 v[70:71], v[66:69], off nt
	v_pk_fma_f32 v[62:63], v[62:63], v[174:175], v[98:99] op_sel_hi:[1,0,1]
	v_pk_fma_f32 v[58:59], v[58:59], v[174:175], v[102:103] op_sel_hi:[1,0,1]
	v_mul_f32_e32 v66, 0xbfb8aa3b, v62
	v_mul_f32_e32 v67, 0xbfb8aa3b, v63
	v_exp_f32_e32 v66, v66
	v_exp_f32_e32 v67, v67
	v_pk_fma_f32 v[60:61], v[60:61], v[174:175], v[104:105] op_sel_hi:[1,0,1]
	v_pk_fma_f32 v[54:55], v[54:55], v[174:175], v[82:83] op_sel_hi:[1,0,1]
	v_add_f32_e32 v66, 1.0, v66
	v_add_f32_e32 v67, 1.0, v67
	v_rcp_f32_e32 v66, v66
	v_rcp_f32_e32 v67, v67
	v_pk_fma_f32 v[50:51], v[50:51], v[174:175], v[86:87] op_sel_hi:[1,0,1]
	v_pk_fma_f32 v[52:53], v[52:53], v[174:175], v[88:89] op_sel_hi:[1,0,1]
	v_pk_mul_f32 v[62:63], v[62:63], v[66:67]
	s_nop 0
	v_pk_mul_f32 v[58:59], v[58:59], v[62:63]
	v_pk_fma_f32 v[62:63], v[64:65], v[174:175], v[100:101] op_sel_hi:[1,0,1]
	s_nop 0
	v_mul_f32_e32 v64, 0xbfb8aa3b, v62
	v_mul_f32_e32 v65, 0xbfb8aa3b, v63
	v_exp_f32_e32 v64, v64
	v_exp_f32_e32 v65, v65
	v_add_f32_e32 v64, 1.0, v64
	v_add_f32_e32 v65, 1.0, v65
	v_rcp_f32_e32 v64, v64
	v_rcp_f32_e32 v65, v65
	s_nop 0
	v_pk_mul_f32 v[62:63], v[62:63], v[64:65]
	s_nop 0
	v_pk_mul_f32 v[60:61], v[60:61], v[62:63]
	v_mul_f32_e32 v62, 0xbfb8aa3b, v54
	v_mul_f32_e32 v63, 0xbfb8aa3b, v55
	v_exp_f32_e32 v62, v62
	v_exp_f32_e32 v63, v63
	v_add_f32_e32 v62, 1.0, v62
	v_add_f32_e32 v63, 1.0, v63
	v_rcp_f32_e32 v62, v62
	v_rcp_f32_e32 v63, v63
	s_nop 0
	v_pk_mul_f32 v[54:55], v[54:55], v[62:63]
	s_nop 0
	v_pk_mul_f32 v[54:55], v[50:51], v[54:55]
	v_pk_fma_f32 v[50:51], v[56:57], v[174:175], v[84:85] op_sel_hi:[1,0,1]
	s_nop 0
	v_mul_f32_e32 v56, 0xbfb8aa3b, v50
	v_mul_f32_e32 v57, 0xbfb8aa3b, v51
	v_exp_f32_e32 v56, v56
	v_exp_f32_e32 v57, v57
	v_add_f32_e32 v56, 1.0, v56
	v_add_f32_e32 v57, 1.0, v57
	v_rcp_f32_e32 v56, v56
	v_rcp_f32_e32 v57, v57
	s_nop 0
	v_pk_mul_f32 v[50:51], v[50:51], v[56:57]
	s_nop 0
	v_pk_mul_f32 v[56:57], v[52:53], v[50:51]
	v_cvt_pk_bf16_f32 v52, v54, v55
	v_lshrrev_b32_e32 v54, 8, v181
	v_mad_i32_i24 v54, v54, 44, v161
	v_ashrrev_i32_e32 v55, 31, v54
	v_cvt_pk_bf16_f32 v53, v56, v57
	v_lshlrev_b64 v[54:55], 15, v[54:55]
	v_lshlrev_b32_e32 v56, 7, v181
	v_lshl_add_u64 v[54:55], s[14:15], 0, v[54:55]
	v_and_b32_e32 v56, 0x7f80, v56
	v_mov_b32_e32 v57, v0
	v_lshl_add_u64 v[54:55], v[54:55], 0, v[56:57]
	v_cvt_pk_bf16_f32 v50, v58, v59
	v_cvt_pk_bf16_f32 v51, v60, v61
	v_lshl_add_u64 v[54:55], v[54:55], 0, v[130:131]
	global_store_dwordx4 v[54:55], v[50:53], off nt
	v_pk_fma_f32 v[46:47], v[46:47], v[172:173], v[98:99] op_sel_hi:[1,0,1]
	v_pk_fma_f32 v[42:43], v[42:43], v[172:173], v[102:103] op_sel_hi:[1,0,1]
	v_mul_f32_e32 v50, 0xbfb8aa3b, v46
	v_mul_f32_e32 v51, 0xbfb8aa3b, v47
	v_exp_f32_e32 v50, v50
	v_exp_f32_e32 v51, v51
	v_pk_fma_f32 v[44:45], v[44:45], v[172:173], v[104:105] op_sel_hi:[1,0,1]
	v_pk_fma_f32 v[38:39], v[38:39], v[172:173], v[82:83] op_sel_hi:[1,0,1]
	v_add_f32_e32 v50, 1.0, v50
	v_add_f32_e32 v51, 1.0, v51
	v_rcp_f32_e32 v50, v50
	v_rcp_f32_e32 v51, v51
	v_pk_fma_f32 v[34:35], v[34:35], v[172:173], v[86:87] op_sel_hi:[1,0,1]
	v_pk_fma_f32 v[36:37], v[36:37], v[172:173], v[88:89] op_sel_hi:[1,0,1]
	v_pk_mul_f32 v[46:47], v[46:47], v[50:51]
	s_nop 0
	v_pk_mul_f32 v[42:43], v[42:43], v[46:47]
	v_pk_fma_f32 v[46:47], v[48:49], v[172:173], v[100:101] op_sel_hi:[1,0,1]
	s_nop 0
	v_mul_f32_e32 v48, 0xbfb8aa3b, v46
	v_mul_f32_e32 v49, 0xbfb8aa3b, v47
	v_exp_f32_e32 v48, v48
	v_exp_f32_e32 v49, v49
	v_add_f32_e32 v48, 1.0, v48
	v_add_f32_e32 v49, 1.0, v49
	v_rcp_f32_e32 v48, v48
	v_rcp_f32_e32 v49, v49
	s_nop 0
	v_pk_mul_f32 v[46:47], v[46:47], v[48:49]
	s_nop 0
	v_pk_mul_f32 v[44:45], v[44:45], v[46:47]
	v_mul_f32_e32 v46, 0xbfb8aa3b, v38
	v_mul_f32_e32 v47, 0xbfb8aa3b, v39
	v_exp_f32_e32 v46, v46
	v_exp_f32_e32 v47, v47
	v_add_f32_e32 v46, 1.0, v46
	v_add_f32_e32 v47, 1.0, v47
	v_rcp_f32_e32 v46, v46
	v_rcp_f32_e32 v47, v47
	s_nop 0
	v_pk_mul_f32 v[38:39], v[38:39], v[46:47]
	s_nop 0
	v_pk_mul_f32 v[38:39], v[34:35], v[38:39]
	v_pk_fma_f32 v[34:35], v[40:41], v[172:173], v[84:85] op_sel_hi:[1,0,1]
	s_nop 0
	v_mul_f32_e32 v40, 0xbfb8aa3b, v34
	v_mul_f32_e32 v41, 0xbfb8aa3b, v35
	v_exp_f32_e32 v40, v40
	v_exp_f32_e32 v41, v41
	v_add_f32_e32 v40, 1.0, v40
	v_add_f32_e32 v41, 1.0, v41
	v_rcp_f32_e32 v40, v40
	v_rcp_f32_e32 v41, v41
	s_nop 0
	v_pk_mul_f32 v[34:35], v[34:35], v[40:41]
	s_nop 0
	v_pk_mul_f32 v[40:41], v[36:37], v[34:35]
	v_cvt_pk_bf16_f32 v36, v38, v39
	v_lshrrev_b32_e32 v38, 8, v179
	v_mad_i32_i24 v38, v38, 44, v161
	v_ashrrev_i32_e32 v39, 31, v38
	v_cvt_pk_bf16_f32 v37, v40, v41
	v_lshlrev_b64 v[38:39], 15, v[38:39]
	v_lshlrev_b32_e32 v40, 7, v179
	v_lshl_add_u64 v[38:39], s[14:15], 0, v[38:39]
	v_and_b32_e32 v40, 0x7f80, v40
	v_mov_b32_e32 v41, v0
	v_lshl_add_u64 v[38:39], v[38:39], 0, v[40:41]
	v_cvt_pk_bf16_f32 v34, v42, v43
	v_cvt_pk_bf16_f32 v35, v44, v45
	v_lshl_add_u64 v[38:39], v[38:39], 0, v[130:131]
	global_store_dwordx4 v[38:39], v[34:37], off nt
	v_pk_fma_f32 v[30:31], v[30:31], v[158:159], v[98:99] op_sel_hi:[1,0,1]
	v_pk_fma_f32 v[26:27], v[26:27], v[158:159], v[102:103] op_sel_hi:[1,0,1]
	v_mul_f32_e32 v34, 0xbfb8aa3b, v30
	v_mul_f32_e32 v35, 0xbfb8aa3b, v31
	v_exp_f32_e32 v34, v34
	v_exp_f32_e32 v35, v35
	v_pk_fma_f32 v[28:29], v[28:29], v[158:159], v[104:105] op_sel_hi:[1,0,1]
	v_pk_fma_f32 v[22:23], v[22:23], v[158:159], v[82:83] op_sel_hi:[1,0,1]
	v_add_f32_e32 v34, 1.0, v34
	v_add_f32_e32 v35, 1.0, v35
	v_rcp_f32_e32 v34, v34
	v_rcp_f32_e32 v35, v35
	v_pk_fma_f32 v[18:19], v[18:19], v[158:159], v[86:87] op_sel_hi:[1,0,1]
	v_pk_fma_f32 v[20:21], v[20:21], v[158:159], v[88:89] op_sel_hi:[1,0,1]
	v_pk_mul_f32 v[30:31], v[30:31], v[34:35]
	s_nop 0
	v_pk_mul_f32 v[26:27], v[26:27], v[30:31]
	v_pk_fma_f32 v[30:31], v[32:33], v[158:159], v[100:101] op_sel_hi:[1,0,1]
	s_nop 0
	v_mul_f32_e32 v32, 0xbfb8aa3b, v30
	v_mul_f32_e32 v33, 0xbfb8aa3b, v31
	v_exp_f32_e32 v32, v32
	v_exp_f32_e32 v33, v33
	v_add_f32_e32 v32, 1.0, v32
	v_add_f32_e32 v33, 1.0, v33
	v_rcp_f32_e32 v32, v32
	v_rcp_f32_e32 v33, v33
	s_nop 0
	v_pk_mul_f32 v[30:31], v[30:31], v[32:33]
	s_nop 0
	v_pk_mul_f32 v[28:29], v[28:29], v[30:31]
	v_mul_f32_e32 v30, 0xbfb8aa3b, v22
	v_mul_f32_e32 v31, 0xbfb8aa3b, v23
	v_exp_f32_e32 v30, v30
	v_exp_f32_e32 v31, v31
	v_add_f32_e32 v30, 1.0, v30
	v_add_f32_e32 v31, 1.0, v31
	v_rcp_f32_e32 v30, v30
	v_rcp_f32_e32 v31, v31
	s_nop 0
	v_pk_mul_f32 v[22:23], v[22:23], v[30:31]
	s_nop 0
	v_pk_mul_f32 v[22:23], v[18:19], v[22:23]
	v_pk_fma_f32 v[18:19], v[24:25], v[158:159], v[84:85] op_sel_hi:[1,0,1]
	s_nop 0
	v_mul_f32_e32 v24, 0xbfb8aa3b, v18
	v_mul_f32_e32 v25, 0xbfb8aa3b, v19
	v_exp_f32_e32 v24, v24
	v_exp_f32_e32 v25, v25
	v_add_f32_e32 v24, 1.0, v24
	v_add_f32_e32 v25, 1.0, v25
	v_rcp_f32_e32 v24, v24
	v_rcp_f32_e32 v25, v25
	s_nop 0
	v_pk_mul_f32 v[18:19], v[18:19], v[24:25]
	s_nop 0
	v_pk_mul_f32 v[24:25], v[20:21], v[18:19]
	v_cvt_pk_bf16_f32 v20, v22, v23
	v_lshrrev_b32_e32 v22, 8, v177
	v_mad_i32_i24 v22, v22, 44, v161
	v_ashrrev_i32_e32 v23, 31, v22
	v_cvt_pk_bf16_f32 v21, v24, v25
	v_lshlrev_b64 v[22:23], 15, v[22:23]
	v_lshlrev_b32_e32 v24, 7, v177
	v_lshl_add_u64 v[22:23], s[14:15], 0, v[22:23]
	v_and_b32_e32 v24, 0x7f80, v24
	v_mov_b32_e32 v25, v0
	v_lshl_add_u64 v[22:23], v[22:23], 0, v[24:25]
	v_cvt_pk_bf16_f32 v18, v26, v27
	v_cvt_pk_bf16_f32 v19, v28, v29
	v_lshl_add_u64 v[22:23], v[22:23], 0, v[130:131]
	global_store_dwordx4 v[22:23], v[18:21], off nt
	v_pk_fma_f32 v[14:15], v[14:15], v[160:161], v[98:99] op_sel_hi:[1,0,1]
	v_pk_fma_f32 v[10:11], v[10:11], v[160:161], v[102:103] op_sel_hi:[1,0,1]
	v_mul_f32_e32 v18, 0xbfb8aa3b, v14
	v_mul_f32_e32 v19, 0xbfb8aa3b, v15
	v_exp_f32_e32 v18, v18
	v_exp_f32_e32 v19, v19
	v_pk_fma_f32 v[12:13], v[12:13], v[160:161], v[104:105] op_sel_hi:[1,0,1]
	v_pk_fma_f32 v[6:7], v[6:7], v[160:161], v[82:83] op_sel_hi:[1,0,1]
	v_add_f32_e32 v18, 1.0, v18
	v_add_f32_e32 v19, 1.0, v19
	v_rcp_f32_e32 v18, v18
	v_rcp_f32_e32 v19, v19
	v_pk_fma_f32 v[2:3], v[2:3], v[160:161], v[86:87] op_sel_hi:[1,0,1]
	v_pk_fma_f32 v[4:5], v[4:5], v[160:161], v[88:89] op_sel_hi:[1,0,1]
	s_and_b64 vcc, exec, s[36:37]
	v_pk_mul_f32 v[14:15], v[14:15], v[18:19]
	s_mov_b32 s42, s4
	v_pk_mul_f32 v[10:11], v[10:11], v[14:15]
	v_pk_fma_f32 v[14:15], v[16:17], v[160:161], v[100:101] op_sel_hi:[1,0,1]
	s_mov_b32 s12, s6
	v_mul_f32_e32 v16, 0xbfb8aa3b, v14
	v_mul_f32_e32 v17, 0xbfb8aa3b, v15
	v_exp_f32_e32 v16, v16
	v_exp_f32_e32 v17, v17
	s_mov_b64 s[16:17], s[10:11]
	v_add_f32_e32 v16, 1.0, v16
	v_add_f32_e32 v17, 1.0, v17
	v_rcp_f32_e32 v16, v16
	v_rcp_f32_e32 v17, v17
	s_nop 0
	v_pk_mul_f32 v[14:15], v[14:15], v[16:17]
	s_nop 0
	v_pk_mul_f32 v[12:13], v[12:13], v[14:15]
	v_mul_f32_e32 v14, 0xbfb8aa3b, v6
	v_mul_f32_e32 v15, 0xbfb8aa3b, v7
	v_exp_f32_e32 v14, v14
	v_exp_f32_e32 v15, v15
	v_add_f32_e32 v14, 1.0, v14
	v_add_f32_e32 v15, 1.0, v15
	v_rcp_f32_e32 v14, v14
	v_rcp_f32_e32 v15, v15
	s_nop 0
	v_pk_mul_f32 v[6:7], v[6:7], v[14:15]
	s_nop 0
	v_pk_mul_f32 v[6:7], v[2:3], v[6:7]
	v_pk_fma_f32 v[2:3], v[8:9], v[160:161], v[84:85] op_sel_hi:[1,0,1]
	s_nop 0
	v_mul_f32_e32 v8, 0xbfb8aa3b, v2
	v_mul_f32_e32 v9, 0xbfb8aa3b, v3
	v_exp_f32_e32 v8, v8
	v_exp_f32_e32 v9, v9
	v_add_f32_e32 v8, 1.0, v8
	v_add_f32_e32 v9, 1.0, v9
	v_rcp_f32_e32 v8, v8
	v_rcp_f32_e32 v9, v9
	s_nop 0
	v_pk_mul_f32 v[2:3], v[2:3], v[8:9]
	s_nop 0
	v_pk_mul_f32 v[8:9], v[4:5], v[2:3]
	v_cvt_pk_bf16_f32 v4, v6, v7
	v_lshrrev_b32_e32 v6, 8, v175
	v_mad_i32_i24 v6, v6, 44, v161
	v_ashrrev_i32_e32 v7, 31, v6
	v_cvt_pk_bf16_f32 v5, v8, v9
	v_lshlrev_b64 v[6:7], 15, v[6:7]
	v_lshlrev_b32_e32 v8, 7, v175
	v_lshl_add_u64 v[6:7], s[14:15], 0, v[6:7]
	v_and_b32_e32 v8, 0x7f80, v8
	v_mov_b32_e32 v9, v0
	v_lshl_add_u64 v[6:7], v[6:7], 0, v[8:9]
	v_cvt_pk_bf16_f32 v2, v10, v11
	v_cvt_pk_bf16_f32 v3, v12, v13
	v_lshl_add_u64 v[6:7], v[6:7], 0, v[130:131]
	s_mov_b64 s[14:15], s[8:9]
	global_store_dwordx4 v[6:7], v[2:5], off nt
	s_cbranch_vccnz .LBB0_625

.LBB0_869:
	s_lshl_b32 s3, s10, 8
	v_mov_b32_e32 v82, v159
	v_mov_b32_e32 v83, v1
	s_add_i32 s3, s3, s27
	v_readlane_b32 s12, v254, 33
	v_add_u32_e32 v182, s3, v82
	s_lshl_b32 s3, s38, 7
	s_or_b32 s3, s3, s28
	v_lshl_add_u32 v186, v83, 3, s3
	s_ashr_i32 s3, s10, 5
	s_mul_hi_i32 s5, s3, 0x5800
	s_mulk_i32 s3, 0x5800
	v_readlane_b32 s13, v254, 34
	s_add_u32 s12, s12, s3
	s_addc_u32 s13, s13, s5
	v_ashrrev_i32_e32 v187, 31, v186
	v_lshl_add_u64 v[86:87], v[186:187], 2, s[12:13]
	s_mov_b64 s[12:13], 0x2c00
	v_lshl_add_u64 v[88:89], v[86:87], 0, s[12:13]
	s_movk_i32 s3, 0x2000
	v_readlane_b32 s12, v254, 31
	global_load_dwordx4 v[82:85], v[86:87], off offset:16
	global_load_dwordx4 v[98:101], v[86:87], off
	v_add_co_u32_e32 v86, vcc, s3, v86
	v_ashrrev_i32_e32 v183, 31, v182
	v_readlane_b32 s13, v254, 32
	v_addc_co_u32_e32 v87, vcc, 0, v87, vcc
	s_nop 0
	v_lshl_add_u64 v[160:161], v[182:183], 2, s[12:13]
	global_load_dwordx4 v[102:105], v[86:87], off offset:3072
	s_nop 0
	global_load_dwordx4 v[86:89], v[88:89], off offset:16
	v_add_u32_e32 v187, 16, v182
	global_load_dword v184, v[160:161], off
	global_load_dword v180, v[160:161], off offset:64
	global_load_dword v178, v[160:161], off offset:128
	global_load_dword v176, v[160:161], off offset:192
	global_load_dword v174, v[160:161], off offset:512
	global_load_dword v172, v[160:161], off offset:576
	global_load_dword v175, v[160:161], off offset:640
	global_load_dword v160, v[160:161], off offset:704
	v_add_u32_e32 v185, 32, v182
	v_add_u32_e32 v183, 48, v182
	v_add_u32_e32 v181, 0x80, v182
	v_add_u32_e32 v179, 0x90, v182
	v_add_u32_e32 v177, 0xa0, v182
	s_waitcnt vmcnt(0)
	v_fmamk_f32 v158, v184, 0x3a800000, v223
	v_cmp_gt_f32_e32 vcc, s95, v158
	v_mul_f32_e32 v168, 0x4b800000, v158
	s_nop 0
	v_cndmask_b32_e32 v158, v158, v168, vcc
	v_rsq_f32_e32 v158, v158
	s_nop 0
	v_mul_f32_e32 v168, 0x45800000, v158
	v_cndmask_b32_e32 v184, v158, v168, vcc
	v_fmamk_f32 v158, v180, 0x3a800000, v223
	v_cmp_gt_f32_e32 vcc, s95, v158
	v_mul_f32_e32 v168, 0x4b800000, v158
	s_nop 0
	v_cndmask_b32_e32 v158, v158, v168, vcc
	v_rsq_f32_e32 v158, v158
	s_nop 0
	v_mul_f32_e32 v168, 0x45800000, v158
	v_cndmask_b32_e32 v180, v158, v168, vcc
	v_fmamk_f32 v158, v178, 0x3a800000, v223
	v_cmp_gt_f32_e32 vcc, s95, v158
	v_mul_f32_e32 v168, 0x4b800000, v158
	s_nop 0
	v_cndmask_b32_e32 v158, v158, v168, vcc
	v_rsq_f32_e32 v158, v158
	s_nop 0
	v_mul_f32_e32 v168, 0x45800000, v158
	v_cndmask_b32_e32 v178, v158, v168, vcc
	v_fmamk_f32 v158, v176, 0x3a800000, v223
	v_cmp_gt_f32_e32 vcc, s95, v158
	v_mul_f32_e32 v168, 0x4b800000, v158
	s_nop 0
	v_cndmask_b32_e32 v158, v158, v168, vcc
	v_rsq_f32_e32 v158, v158
	s_nop 0
	v_mul_f32_e32 v168, 0x45800000, v158
	v_cndmask_b32_e32 v176, v158, v168, vcc
	v_fmamk_f32 v158, v174, 0x3a800000, v223
	v_cmp_gt_f32_e32 vcc, s95, v158
	v_mul_f32_e32 v168, 0x4b800000, v158
	s_nop 0
	v_cndmask_b32_e32 v158, v158, v168, vcc
	v_rsq_f32_e32 v158, v158
	s_nop 0
	v_mul_f32_e32 v168, 0x45800000, v158
	v_cndmask_b32_e32 v174, v158, v168, vcc
	v_fmamk_f32 v158, v172, 0x3a800000, v223
	v_cmp_gt_f32_e32 vcc, s95, v158
	v_mul_f32_e32 v168, 0x4b800000, v158
	s_nop 0
	v_cndmask_b32_e32 v158, v158, v168, vcc
	v_rsq_f32_e32 v158, v158
	s_nop 0
	v_mul_f32_e32 v168, 0x45800000, v158
	v_cndmask_b32_e32 v172, v158, v168, vcc
	v_fmamk_f32 v158, v175, 0x3a800000, v223
	v_add_u32_e32 v175, 0xb0, v182
	v_cmp_gt_f32_e32 vcc, s95, v158
	v_mul_f32_e32 v168, 0x4b800000, v158
	v_fmamk_f32 v160, v160, 0x3a800000, v223
	v_cndmask_b32_e32 v158, v158, v168, vcc
	v_rsq_f32_e32 v158, v158
	v_mul_f32_e32 v161, 0x4b800000, v160
	v_mul_f32_e32 v168, 0x45800000, v158
	v_cndmask_b32_e32 v158, v158, v168, vcc
	v_cmp_gt_f32_e32 vcc, s95, v160
	v_and_b32_e32 v168, 56, v186
	s_nop 0
	v_cndmask_b32_e32 v160, v160, v161, vcc
	v_rsq_f32_e32 v160, v160
	s_nop 0
	v_mul_f32_e32 v161, 0x45800000, v160
	v_cndmask_b32_e32 v160, v160, v161, vcc
	v_ashrrev_i32_e32 v161, 6, v186
	v_pk_fma_f32 v[138:139], v[138:139], v[184:185], v[98:99] op_sel_hi:[1,0,1]
	v_pk_fma_f32 v[142:143], v[142:143], v[184:185], v[102:103] op_sel_hi:[1,0,1]
	v_mul_f32_e32 v169, 0xbfb8aa3b, v138
	v_exp_f32_e32 v169, v169
	v_pk_fma_f32 v[140:141], v[140:141], v[184:185], v[100:101] op_sel_hi:[1,0,1]
	v_pk_fma_f32 v[134:135], v[134:135], v[184:185], v[82:83] op_sel_hi:[1,0,1]
	v_pk_fma_f32 v[130:131], v[130:131], v[184:185], v[86:87] op_sel_hi:[1,0,1]
	v_add_f32_e32 v169, 1.0, v169
	v_rcp_f32_e32 v188, v169
	v_mul_f32_e32 v169, 0xbfb8aa3b, v139
	v_exp_f32_e32 v169, v169
	v_pk_fma_f32 v[132:133], v[132:133], v[184:185], v[88:89] op_sel_hi:[1,0,1]
	v_readlane_b32 s12, v254, 27
	v_readlane_b32 s13, v254, 28
	v_add_f32_e32 v169, 1.0, v169
	v_rcp_f32_e32 v189, v169
	s_nop 0
	v_pk_mul_f32 v[138:139], v[138:139], v[188:189]
	s_nop 0
	v_pk_mul_f32 v[138:139], v[142:143], v[138:139]
	v_pk_fma_f32 v[142:143], v[144:145], v[184:185], v[104:105] op_sel_hi:[1,0,1]
	v_mul_f32_e32 v144, 0xbfb8aa3b, v140
	v_mul_f32_e32 v145, 0xbfb8aa3b, v141
	v_exp_f32_e32 v144, v144
	v_exp_f32_e32 v145, v145
	v_add_f32_e32 v144, 1.0, v144
	v_add_f32_e32 v145, 1.0, v145
	v_rcp_f32_e32 v144, v144
	v_rcp_f32_e32 v145, v145
	s_nop 0
	v_pk_mul_f32 v[140:141], v[140:141], v[144:145]
	s_nop 0
	v_pk_mul_f32 v[140:141], v[142:143], v[140:141]
	v_mul_f32_e32 v142, 0xbfb8aa3b, v134
	v_mul_f32_e32 v143, 0xbfb8aa3b, v135
	v_exp_f32_e32 v142, v142
	v_exp_f32_e32 v143, v143
	v_add_f32_e32 v142, 1.0, v142
	v_add_f32_e32 v143, 1.0, v143
	v_rcp_f32_e32 v142, v142
	v_rcp_f32_e32 v143, v143
	s_nop 0
	v_pk_mul_f32 v[134:135], v[134:135], v[142:143]
	s_nop 0
	v_pk_mul_f32 v[130:131], v[130:131], v[134:135]
	v_pk_fma_f32 v[134:135], v[136:137], v[184:185], v[84:85] op_sel_hi:[1,0,1]
	s_nop 0
	v_mul_f32_e32 v136, 0xbfb8aa3b, v134
	v_mul_f32_e32 v137, 0xbfb8aa3b, v135
	v_exp_f32_e32 v136, v136
	v_exp_f32_e32 v137, v137
	v_add_f32_e32 v136, 1.0, v136
	v_add_f32_e32 v137, 1.0, v137
	v_rcp_f32_e32 v136, v136
	v_rcp_f32_e32 v137, v137
	s_nop 0
	v_pk_mul_f32 v[134:135], v[134:135], v[136:137]
	s_nop 0
	v_pk_mul_f32 v[136:137], v[132:133], v[134:135]
	v_cvt_pk_bf16_f32 v134, v130, v131
	v_lshrrev_b32_e32 v130, 8, v182
	v_mad_i32_i24 v130, v130, 44, v161
	v_ashrrev_i32_e32 v131, 31, v130
	v_cvt_pk_bf16_f32 v135, v136, v137
	v_lshlrev_b64 v[130:131], 15, v[130:131]
	v_lshlrev_b32_e32 v136, 7, v182
	v_lshl_add_u64 v[130:131], s[12:13], 0, v[130:131]
	v_and_b32_e32 v136, 0x7f80, v136
	v_mov_b32_e32 v137, v0
	v_lshl_add_u64 v[136:137], v[130:131], 0, v[136:137]
	v_lshlrev_b32_e32 v130, 1, v168
	v_mov_b32_e32 v131, v0
	v_cvt_pk_bf16_f32 v132, v138, v139
	v_cvt_pk_bf16_f32 v133, v140, v141
	v_lshl_add_u64 v[136:137], v[136:137], 0, v[130:131]
	global_store_dwordx4 v[136:137], v[132:135], off nt
	v_pk_fma_f32 v[126:127], v[126:127], v[180:181], v[98:99] op_sel_hi:[1,0,1]
	v_pk_fma_f32 v[122:123], v[122:123], v[180:181], v[102:103] op_sel_hi:[1,0,1]
	v_mul_f32_e32 v132, 0xbfb8aa3b, v126
	v_mul_f32_e32 v133, 0xbfb8aa3b, v127
	v_exp_f32_e32 v132, v132
	v_exp_f32_e32 v133, v133
	v_pk_fma_f32 v[124:125], v[124:125], v[180:181], v[104:105] op_sel_hi:[1,0,1]
	v_pk_fma_f32 v[118:119], v[118:119], v[180:181], v[82:83] op_sel_hi:[1,0,1]
	v_add_f32_e32 v132, 1.0, v132
	v_add_f32_e32 v133, 1.0, v133
	v_rcp_f32_e32 v132, v132
	v_rcp_f32_e32 v133, v133
	v_pk_fma_f32 v[114:115], v[114:115], v[180:181], v[86:87] op_sel_hi:[1,0,1]
	v_pk_fma_f32 v[116:117], v[116:117], v[180:181], v[88:89] op_sel_hi:[1,0,1]
	v_pk_mul_f32 v[126:127], v[126:127], v[132:133]
	s_nop 0
	v_pk_mul_f32 v[122:123], v[122:123], v[126:127]
	v_pk_fma_f32 v[126:127], v[128:129], v[180:181], v[100:101] op_sel_hi:[1,0,1]
	s_nop 0
	v_mul_f32_e32 v128, 0xbfb8aa3b, v126
	v_mul_f32_e32 v129, 0xbfb8aa3b, v127
	v_exp_f32_e32 v128, v128
	v_exp_f32_e32 v129, v129
	v_add_f32_e32 v128, 1.0, v128
	v_add_f32_e32 v129, 1.0, v129
	v_rcp_f32_e32 v128, v128
	v_rcp_f32_e32 v129, v129
	s_nop 0
	v_pk_mul_f32 v[126:127], v[126:127], v[128:129]
	s_nop 0
	v_pk_mul_f32 v[124:125], v[124:125], v[126:127]
	v_mul_f32_e32 v126, 0xbfb8aa3b, v118
	v_mul_f32_e32 v127, 0xbfb8aa3b, v119
	v_exp_f32_e32 v126, v126
	v_exp_f32_e32 v127, v127
	v_add_f32_e32 v126, 1.0, v126
	v_add_f32_e32 v127, 1.0, v127
	v_rcp_f32_e32 v126, v126
	v_rcp_f32_e32 v127, v127
	s_nop 0
	v_pk_mul_f32 v[118:119], v[118:119], v[126:127]
	s_nop 0
	v_pk_mul_f32 v[118:119], v[114:115], v[118:119]
	v_pk_fma_f32 v[114:115], v[120:121], v[180:181], v[84:85] op_sel_hi:[1,0,1]
	s_nop 0
	v_mul_f32_e32 v120, 0xbfb8aa3b, v114
	v_mul_f32_e32 v121, 0xbfb8aa3b, v115
	v_exp_f32_e32 v120, v120
	v_exp_f32_e32 v121, v121
	v_add_f32_e32 v120, 1.0, v120
	v_add_f32_e32 v121, 1.0, v121
	v_rcp_f32_e32 v120, v120
	v_rcp_f32_e32 v121, v121
	s_nop 0
	v_pk_mul_f32 v[114:115], v[114:115], v[120:121]
	s_nop 0
	v_pk_mul_f32 v[120:121], v[116:117], v[114:115]
	v_cvt_pk_bf16_f32 v116, v118, v119
	v_lshrrev_b32_e32 v118, 8, v187
	v_mad_i32_i24 v118, v118, 44, v161
	v_ashrrev_i32_e32 v119, 31, v118
	v_cvt_pk_bf16_f32 v117, v120, v121
	v_lshlrev_b64 v[118:119], 15, v[118:119]
	v_lshlrev_b32_e32 v120, 7, v187
	v_lshl_add_u64 v[118:119], s[12:13], 0, v[118:119]
	v_and_b32_e32 v120, 0x7f80, v120
	v_mov_b32_e32 v121, v0
	v_lshl_add_u64 v[118:119], v[118:119], 0, v[120:121]
	v_cvt_pk_bf16_f32 v114, v122, v123
	v_cvt_pk_bf16_f32 v115, v124, v125
	v_lshl_add_u64 v[118:119], v[118:119], 0, v[130:131]
	global_store_dwordx4 v[118:119], v[114:117], off nt
	v_pk_fma_f32 v[110:111], v[110:111], v[178:179], v[98:99] op_sel_hi:[1,0,1]
	v_pk_fma_f32 v[106:107], v[106:107], v[178:179], v[102:103] op_sel_hi:[1,0,1]
	v_mul_f32_e32 v114, 0xbfb8aa3b, v110
	v_mul_f32_e32 v115, 0xbfb8aa3b, v111
	v_exp_f32_e32 v114, v114
	v_exp_f32_e32 v115, v115
	v_pk_fma_f32 v[108:109], v[108:109], v[178:179], v[104:105] op_sel_hi:[1,0,1]
	v_pk_fma_f32 v[94:95], v[94:95], v[178:179], v[82:83] op_sel_hi:[1,0,1]
	v_add_f32_e32 v114, 1.0, v114
	v_add_f32_e32 v115, 1.0, v115
	v_rcp_f32_e32 v114, v114
	v_rcp_f32_e32 v115, v115
	v_pk_fma_f32 v[90:91], v[90:91], v[178:179], v[86:87] op_sel_hi:[1,0,1]
	v_pk_fma_f32 v[92:93], v[92:93], v[178:179], v[88:89] op_sel_hi:[1,0,1]
	v_pk_mul_f32 v[110:111], v[110:111], v[114:115]
	s_nop 0
	v_pk_mul_f32 v[106:107], v[106:107], v[110:111]
	v_pk_fma_f32 v[110:111], v[112:113], v[178:179], v[100:101] op_sel_hi:[1,0,1]
	s_nop 0
	v_mul_f32_e32 v112, 0xbfb8aa3b, v110
	v_mul_f32_e32 v113, 0xbfb8aa3b, v111
	v_exp_f32_e32 v112, v112
	v_exp_f32_e32 v113, v113
	v_add_f32_e32 v112, 1.0, v112
	v_add_f32_e32 v113, 1.0, v113
	v_rcp_f32_e32 v112, v112
	v_rcp_f32_e32 v113, v113
	s_nop 0
	v_pk_mul_f32 v[110:111], v[110:111], v[112:113]
	s_nop 0
	v_pk_mul_f32 v[108:109], v[108:109], v[110:111]
	v_mul_f32_e32 v110, 0xbfb8aa3b, v94
	v_mul_f32_e32 v111, 0xbfb8aa3b, v95
	v_exp_f32_e32 v110, v110
	v_exp_f32_e32 v111, v111
	v_add_f32_e32 v110, 1.0, v110
	v_add_f32_e32 v111, 1.0, v111
	v_rcp_f32_e32 v110, v110
	v_rcp_f32_e32 v111, v111
	s_nop 0
	v_pk_mul_f32 v[94:95], v[94:95], v[110:111]
	s_nop 0
	v_pk_mul_f32 v[94:95], v[90:91], v[94:95]
	v_pk_fma_f32 v[90:91], v[96:97], v[178:179], v[84:85] op_sel_hi:[1,0,1]
	s_nop 0
	v_mul_f32_e32 v96, 0xbfb8aa3b, v90
	v_mul_f32_e32 v97, 0xbfb8aa3b, v91
	v_exp_f32_e32 v96, v96
	v_exp_f32_e32 v97, v97
	v_add_f32_e32 v96, 1.0, v96
	v_add_f32_e32 v97, 1.0, v97
	v_rcp_f32_e32 v96, v96
	v_rcp_f32_e32 v97, v97
	s_nop 0
	v_pk_mul_f32 v[90:91], v[90:91], v[96:97]
	s_nop 0
	v_pk_mul_f32 v[96:97], v[92:93], v[90:91]
	v_cvt_pk_bf16_f32 v92, v94, v95
	v_lshrrev_b32_e32 v94, 8, v185
	v_mad_i32_i24 v94, v94, 44, v161
	v_ashrrev_i32_e32 v95, 31, v94
	v_cvt_pk_bf16_f32 v93, v96, v97
	v_lshlrev_b64 v[94:95], 15, v[94:95]
	v_lshlrev_b32_e32 v96, 7, v185
	v_lshl_add_u64 v[94:95], s[12:13], 0, v[94:95]
	v_and_b32_e32 v96, 0x7f80, v96
	v_mov_b32_e32 v97, v0
	v_lshl_add_u64 v[94:95], v[94:95], 0, v[96:97]
	v_cvt_pk_bf16_f32 v90, v106, v107
	v_cvt_pk_bf16_f32 v91, v108, v109
	v_lshl_add_u64 v[94:95], v[94:95], 0, v[130:131]
	global_store_dwordx4 v[94:95], v[90:93], off nt
	v_pk_fma_f32 v[78:79], v[78:79], v[176:177], v[98:99] op_sel_hi:[1,0,1]
	v_pk_fma_f32 v[74:75], v[74:75], v[176:177], v[102:103] op_sel_hi:[1,0,1]
	v_mul_f32_e32 v90, 0xbfb8aa3b, v78
	v_mul_f32_e32 v91, 0xbfb8aa3b, v79
	v_exp_f32_e32 v90, v90
	v_exp_f32_e32 v91, v91
	v_pk_fma_f32 v[76:77], v[76:77], v[176:177], v[104:105] op_sel_hi:[1,0,1]
	v_pk_fma_f32 v[70:71], v[70:71], v[176:177], v[82:83] op_sel_hi:[1,0,1]
	v_add_f32_e32 v90, 1.0, v90
	v_add_f32_e32 v91, 1.0, v91
	v_rcp_f32_e32 v90, v90
	v_rcp_f32_e32 v91, v91
	v_pk_fma_f32 v[66:67], v[66:67], v[176:177], v[86:87] op_sel_hi:[1,0,1]
	v_pk_fma_f32 v[68:69], v[68:69], v[176:177], v[88:89] op_sel_hi:[1,0,1]
	v_pk_mul_f32 v[78:79], v[78:79], v[90:91]
	s_nop 0
	v_pk_mul_f32 v[74:75], v[74:75], v[78:79]
	v_pk_fma_f32 v[78:79], v[80:81], v[176:177], v[100:101] op_sel_hi:[1,0,1]
	s_nop 0
	v_mul_f32_e32 v80, 0xbfb8aa3b, v78
	v_mul_f32_e32 v81, 0xbfb8aa3b, v79
	v_exp_f32_e32 v80, v80
	v_exp_f32_e32 v81, v81
	v_add_f32_e32 v80, 1.0, v80
	v_add_f32_e32 v81, 1.0, v81
	v_rcp_f32_e32 v80, v80
	v_rcp_f32_e32 v81, v81
	s_nop 0
	v_pk_mul_f32 v[78:79], v[78:79], v[80:81]
	s_nop 0
	v_pk_mul_f32 v[76:77], v[76:77], v[78:79]
	v_mul_f32_e32 v78, 0xbfb8aa3b, v70
	v_mul_f32_e32 v79, 0xbfb8aa3b, v71
	v_exp_f32_e32 v78, v78
	v_exp_f32_e32 v79, v79
	v_add_f32_e32 v78, 1.0, v78
	v_add_f32_e32 v79, 1.0, v79
	v_rcp_f32_e32 v78, v78
	v_rcp_f32_e32 v79, v79
	s_nop 0
	v_pk_mul_f32 v[70:71], v[70:71], v[78:79]
	s_nop 0
	v_pk_mul_f32 v[70:71], v[66:67], v[70:71]
	v_pk_fma_f32 v[66:67], v[72:73], v[176:177], v[84:85] op_sel_hi:[1,0,1]
	s_nop 0
	v_mul_f32_e32 v72, 0xbfb8aa3b, v66
	v_mul_f32_e32 v73, 0xbfb8aa3b, v67
	v_exp_f32_e32 v72, v72
	v_exp_f32_e32 v73, v73
	v_add_f32_e32 v72, 1.0, v72
	v_add_f32_e32 v73, 1.0, v73
	v_rcp_f32_e32 v72, v72
	v_rcp_f32_e32 v73, v73
	s_nop 0
	v_pk_mul_f32 v[66:67], v[66:67], v[72:73]
	s_nop 0
	v_pk_mul_f32 v[72:73], v[68:69], v[66:67]
	v_cvt_pk_bf16_f32 v68, v70, v71
	v_lshrrev_b32_e32 v70, 8, v183
	v_mad_i32_i24 v70, v70, 44, v161
	v_ashrrev_i32_e32 v71, 31, v70
	v_cvt_pk_bf16_f32 v69, v72, v73
	v_lshlrev_b64 v[70:71], 15, v[70:71]
	v_lshlrev_b32_e32 v72, 7, v183
	v_lshl_add_u64 v[70:71], s[12:13], 0, v[70:71]
	v_and_b32_e32 v72, 0x7f80, v72
	v_mov_b32_e32 v73, v0
	v_lshl_add_u64 v[70:71], v[70:71], 0, v[72:73]
	v_cvt_pk_bf16_f32 v66, v74, v75
	v_cvt_pk_bf16_f32 v67, v76, v77
	v_lshl_add_u64 v[70:71], v[70:71], 0, v[130:131]
	global_store_dwordx4 v[70:71], v[66:69], off nt
	v_pk_fma_f32 v[62:63], v[62:63], v[174:175], v[98:99] op_sel_hi:[1,0,1]
	v_pk_fma_f32 v[58:59], v[58:59], v[174:175], v[102:103] op_sel_hi:[1,0,1]
	v_mul_f32_e32 v66, 0xbfb8aa3b, v62
	v_mul_f32_e32 v67, 0xbfb8aa3b, v63
	v_exp_f32_e32 v66, v66
	v_exp_f32_e32 v67, v67
	v_pk_fma_f32 v[60:61], v[60:61], v[174:175], v[104:105] op_sel_hi:[1,0,1]
	v_pk_fma_f32 v[54:55], v[54:55], v[174:175], v[82:83] op_sel_hi:[1,0,1]
	v_add_f32_e32 v66, 1.0, v66
	v_add_f32_e32 v67, 1.0, v67
	v_rcp_f32_e32 v66, v66
	v_rcp_f32_e32 v67, v67
	v_pk_fma_f32 v[50:51], v[50:51], v[174:175], v[86:87] op_sel_hi:[1,0,1]
	v_pk_fma_f32 v[52:53], v[52:53], v[174:175], v[88:89] op_sel_hi:[1,0,1]
	v_pk_mul_f32 v[62:63], v[62:63], v[66:67]
	s_nop 0
	v_pk_mul_f32 v[58:59], v[58:59], v[62:63]
	v_pk_fma_f32 v[62:63], v[64:65], v[174:175], v[100:101] op_sel_hi:[1,0,1]
	s_nop 0
	v_mul_f32_e32 v64, 0xbfb8aa3b, v62
	v_mul_f32_e32 v65, 0xbfb8aa3b, v63
	v_exp_f32_e32 v64, v64
	v_exp_f32_e32 v65, v65
	v_add_f32_e32 v64, 1.0, v64
	v_add_f32_e32 v65, 1.0, v65
	v_rcp_f32_e32 v64, v64
	v_rcp_f32_e32 v65, v65
	s_nop 0
	v_pk_mul_f32 v[62:63], v[62:63], v[64:65]
	s_nop 0
	v_pk_mul_f32 v[60:61], v[60:61], v[62:63]
	v_mul_f32_e32 v62, 0xbfb8aa3b, v54
	v_mul_f32_e32 v63, 0xbfb8aa3b, v55
	v_exp_f32_e32 v62, v62
	v_exp_f32_e32 v63, v63
	v_add_f32_e32 v62, 1.0, v62
	v_add_f32_e32 v63, 1.0, v63
	v_rcp_f32_e32 v62, v62
	v_rcp_f32_e32 v63, v63
	s_nop 0
	v_pk_mul_f32 v[54:55], v[54:55], v[62:63]
	s_nop 0
	v_pk_mul_f32 v[54:55], v[50:51], v[54:55]
	v_pk_fma_f32 v[50:51], v[56:57], v[174:175], v[84:85] op_sel_hi:[1,0,1]
	s_nop 0
	v_mul_f32_e32 v56, 0xbfb8aa3b, v50
	v_mul_f32_e32 v57, 0xbfb8aa3b, v51
	v_exp_f32_e32 v56, v56
	v_exp_f32_e32 v57, v57
	v_add_f32_e32 v56, 1.0, v56
	v_add_f32_e32 v57, 1.0, v57
	v_rcp_f32_e32 v56, v56
	v_rcp_f32_e32 v57, v57
	s_nop 0
	v_pk_mul_f32 v[50:51], v[50:51], v[56:57]
	s_nop 0
	v_pk_mul_f32 v[56:57], v[52:53], v[50:51]
	v_cvt_pk_bf16_f32 v52, v54, v55
	v_lshrrev_b32_e32 v54, 8, v181
	v_mad_i32_i24 v54, v54, 44, v161
	v_ashrrev_i32_e32 v55, 31, v54
	v_cvt_pk_bf16_f32 v53, v56, v57
	v_lshlrev_b64 v[54:55], 15, v[54:55]
	v_lshlrev_b32_e32 v56, 7, v181
	v_lshl_add_u64 v[54:55], s[12:13], 0, v[54:55]
	v_and_b32_e32 v56, 0x7f80, v56
	v_mov_b32_e32 v57, v0
	v_lshl_add_u64 v[54:55], v[54:55], 0, v[56:57]
	v_cvt_pk_bf16_f32 v50, v58, v59
	v_cvt_pk_bf16_f32 v51, v60, v61
	v_lshl_add_u64 v[54:55], v[54:55], 0, v[130:131]
	global_store_dwordx4 v[54:55], v[50:53], off nt
	v_pk_fma_f32 v[46:47], v[46:47], v[172:173], v[98:99] op_sel_hi:[1,0,1]
	v_pk_fma_f32 v[42:43], v[42:43], v[172:173], v[102:103] op_sel_hi:[1,0,1]
	v_mul_f32_e32 v50, 0xbfb8aa3b, v46
	v_mul_f32_e32 v51, 0xbfb8aa3b, v47
	v_exp_f32_e32 v50, v50
	v_exp_f32_e32 v51, v51
	v_pk_fma_f32 v[44:45], v[44:45], v[172:173], v[104:105] op_sel_hi:[1,0,1]
	v_pk_fma_f32 v[38:39], v[38:39], v[172:173], v[82:83] op_sel_hi:[1,0,1]
	v_add_f32_e32 v50, 1.0, v50
	v_add_f32_e32 v51, 1.0, v51
	v_rcp_f32_e32 v50, v50
	v_rcp_f32_e32 v51, v51
	v_pk_fma_f32 v[34:35], v[34:35], v[172:173], v[86:87] op_sel_hi:[1,0,1]
	v_pk_fma_f32 v[36:37], v[36:37], v[172:173], v[88:89] op_sel_hi:[1,0,1]
	v_pk_mul_f32 v[46:47], v[46:47], v[50:51]
	s_nop 0
	v_pk_mul_f32 v[42:43], v[42:43], v[46:47]
	v_pk_fma_f32 v[46:47], v[48:49], v[172:173], v[100:101] op_sel_hi:[1,0,1]
	s_nop 0
	v_mul_f32_e32 v48, 0xbfb8aa3b, v46
	v_mul_f32_e32 v49, 0xbfb8aa3b, v47
	v_exp_f32_e32 v48, v48
	v_exp_f32_e32 v49, v49
	v_add_f32_e32 v48, 1.0, v48
	v_add_f32_e32 v49, 1.0, v49
	v_rcp_f32_e32 v48, v48
	v_rcp_f32_e32 v49, v49
	s_nop 0
	v_pk_mul_f32 v[46:47], v[46:47], v[48:49]
	s_nop 0
	v_pk_mul_f32 v[44:45], v[44:45], v[46:47]
	v_mul_f32_e32 v46, 0xbfb8aa3b, v38
	v_mul_f32_e32 v47, 0xbfb8aa3b, v39
	v_exp_f32_e32 v46, v46
	v_exp_f32_e32 v47, v47
	v_add_f32_e32 v46, 1.0, v46
	v_add_f32_e32 v47, 1.0, v47
	v_rcp_f32_e32 v46, v46
	v_rcp_f32_e32 v47, v47
	s_nop 0
	v_pk_mul_f32 v[38:39], v[38:39], v[46:47]
	s_nop 0
	v_pk_mul_f32 v[38:39], v[34:35], v[38:39]
	v_pk_fma_f32 v[34:35], v[40:41], v[172:173], v[84:85] op_sel_hi:[1,0,1]
	s_nop 0
	v_mul_f32_e32 v40, 0xbfb8aa3b, v34
	v_mul_f32_e32 v41, 0xbfb8aa3b, v35
	v_exp_f32_e32 v40, v40
	v_exp_f32_e32 v41, v41
	v_add_f32_e32 v40, 1.0, v40
	v_add_f32_e32 v41, 1.0, v41
	v_rcp_f32_e32 v40, v40
	v_rcp_f32_e32 v41, v41
	s_nop 0
	v_pk_mul_f32 v[34:35], v[34:35], v[40:41]
	s_nop 0
	v_pk_mul_f32 v[40:41], v[36:37], v[34:35]
	v_cvt_pk_bf16_f32 v36, v38, v39
	v_lshrrev_b32_e32 v38, 8, v179
	v_mad_i32_i24 v38, v38, 44, v161
	v_ashrrev_i32_e32 v39, 31, v38
	v_cvt_pk_bf16_f32 v37, v40, v41
	v_lshlrev_b64 v[38:39], 15, v[38:39]
	v_lshlrev_b32_e32 v40, 7, v179
	v_lshl_add_u64 v[38:39], s[12:13], 0, v[38:39]
	v_and_b32_e32 v40, 0x7f80, v40
	v_mov_b32_e32 v41, v0
	v_lshl_add_u64 v[38:39], v[38:39], 0, v[40:41]
	v_cvt_pk_bf16_f32 v34, v42, v43
	v_cvt_pk_bf16_f32 v35, v44, v45
	v_lshl_add_u64 v[38:39], v[38:39], 0, v[130:131]
	global_store_dwordx4 v[38:39], v[34:37], off nt
	v_pk_fma_f32 v[30:31], v[30:31], v[158:159], v[98:99] op_sel_hi:[1,0,1]
	v_pk_fma_f32 v[26:27], v[26:27], v[158:159], v[102:103] op_sel_hi:[1,0,1]
	v_mul_f32_e32 v34, 0xbfb8aa3b, v30
	v_mul_f32_e32 v35, 0xbfb8aa3b, v31
	v_exp_f32_e32 v34, v34
	v_exp_f32_e32 v35, v35
	v_pk_fma_f32 v[28:29], v[28:29], v[158:159], v[104:105] op_sel_hi:[1,0,1]
	v_pk_fma_f32 v[22:23], v[22:23], v[158:159], v[82:83] op_sel_hi:[1,0,1]
	v_add_f32_e32 v34, 1.0, v34
	v_add_f32_e32 v35, 1.0, v35
	v_rcp_f32_e32 v34, v34
	v_rcp_f32_e32 v35, v35
	v_pk_fma_f32 v[18:19], v[18:19], v[158:159], v[86:87] op_sel_hi:[1,0,1]
	v_pk_fma_f32 v[20:21], v[20:21], v[158:159], v[88:89] op_sel_hi:[1,0,1]
	v_pk_mul_f32 v[30:31], v[30:31], v[34:35]
	s_nop 0
	v_pk_mul_f32 v[26:27], v[26:27], v[30:31]
	v_pk_fma_f32 v[30:31], v[32:33], v[158:159], v[100:101] op_sel_hi:[1,0,1]
	s_nop 0
	v_mul_f32_e32 v32, 0xbfb8aa3b, v30
	v_mul_f32_e32 v33, 0xbfb8aa3b, v31
	v_exp_f32_e32 v32, v32
	v_exp_f32_e32 v33, v33
	v_add_f32_e32 v32, 1.0, v32
	v_add_f32_e32 v33, 1.0, v33
	v_rcp_f32_e32 v32, v32
	v_rcp_f32_e32 v33, v33
	s_nop 0
	v_pk_mul_f32 v[30:31], v[30:31], v[32:33]
	s_nop 0
	v_pk_mul_f32 v[28:29], v[28:29], v[30:31]
	v_mul_f32_e32 v30, 0xbfb8aa3b, v22
	v_mul_f32_e32 v31, 0xbfb8aa3b, v23
	v_exp_f32_e32 v30, v30
	v_exp_f32_e32 v31, v31
	v_add_f32_e32 v30, 1.0, v30
	v_add_f32_e32 v31, 1.0, v31
	v_rcp_f32_e32 v30, v30
	v_rcp_f32_e32 v31, v31
	s_nop 0
	v_pk_mul_f32 v[22:23], v[22:23], v[30:31]
	s_nop 0
	v_pk_mul_f32 v[22:23], v[18:19], v[22:23]
	v_pk_fma_f32 v[18:19], v[24:25], v[158:159], v[84:85] op_sel_hi:[1,0,1]
	s_nop 0
	v_mul_f32_e32 v24, 0xbfb8aa3b, v18
	v_mul_f32_e32 v25, 0xbfb8aa3b, v19
	v_exp_f32_e32 v24, v24
	v_exp_f32_e32 v25, v25
	v_add_f32_e32 v24, 1.0, v24
	v_add_f32_e32 v25, 1.0, v25
	v_rcp_f32_e32 v24, v24
	v_rcp_f32_e32 v25, v25
	s_nop 0
	v_pk_mul_f32 v[18:19], v[18:19], v[24:25]
	s_nop 0
	v_pk_mul_f32 v[24:25], v[20:21], v[18:19]
	v_cvt_pk_bf16_f32 v20, v22, v23
	v_lshrrev_b32_e32 v22, 8, v177
	v_mad_i32_i24 v22, v22, 44, v161
	v_ashrrev_i32_e32 v23, 31, v22
	v_cvt_pk_bf16_f32 v21, v24, v25
	v_lshlrev_b64 v[22:23], 15, v[22:23]
	v_lshlrev_b32_e32 v24, 7, v177
	v_lshl_add_u64 v[22:23], s[12:13], 0, v[22:23]
	v_and_b32_e32 v24, 0x7f80, v24
	v_mov_b32_e32 v25, v0
	v_lshl_add_u64 v[22:23], v[22:23], 0, v[24:25]
	v_cvt_pk_bf16_f32 v18, v26, v27
	v_cvt_pk_bf16_f32 v19, v28, v29
	v_lshl_add_u64 v[22:23], v[22:23], 0, v[130:131]
	global_store_dwordx4 v[22:23], v[18:21], off nt
	v_pk_fma_f32 v[14:15], v[14:15], v[160:161], v[98:99] op_sel_hi:[1,0,1]
	v_pk_fma_f32 v[10:11], v[10:11], v[160:161], v[102:103] op_sel_hi:[1,0,1]
	v_mul_f32_e32 v18, 0xbfb8aa3b, v14
	v_mul_f32_e32 v19, 0xbfb8aa3b, v15
	v_exp_f32_e32 v18, v18
	v_exp_f32_e32 v19, v19
	v_pk_fma_f32 v[12:13], v[12:13], v[160:161], v[104:105] op_sel_hi:[1,0,1]
	v_pk_fma_f32 v[6:7], v[6:7], v[160:161], v[82:83] op_sel_hi:[1,0,1]
	v_add_f32_e32 v18, 1.0, v18
	v_add_f32_e32 v19, 1.0, v19
	v_rcp_f32_e32 v18, v18
	v_rcp_f32_e32 v19, v19
	v_pk_fma_f32 v[2:3], v[2:3], v[160:161], v[86:87] op_sel_hi:[1,0,1]
	v_pk_fma_f32 v[4:5], v[4:5], v[160:161], v[88:89] op_sel_hi:[1,0,1]
	s_and_b64 vcc, exec, s[36:37]
	v_pk_mul_f32 v[14:15], v[14:15], v[18:19]
	s_mov_b32 s38, s2
	v_pk_mul_f32 v[10:11], v[10:11], v[14:15]
	v_pk_fma_f32 v[14:15], v[16:17], v[160:161], v[100:101] op_sel_hi:[1,0,1]
	s_mov_b32 s10, s4
	v_mul_f32_e32 v16, 0xbfb8aa3b, v14
	v_mul_f32_e32 v17, 0xbfb8aa3b, v15
	v_exp_f32_e32 v16, v16
	v_exp_f32_e32 v17, v17
	s_mov_b64 s[14:15], s[8:9]
	v_add_f32_e32 v16, 1.0, v16
	v_add_f32_e32 v17, 1.0, v17
	v_rcp_f32_e32 v16, v16
	v_rcp_f32_e32 v17, v17
	s_nop 0
	v_pk_mul_f32 v[14:15], v[14:15], v[16:17]
	s_nop 0
	v_pk_mul_f32 v[12:13], v[12:13], v[14:15]
	v_mul_f32_e32 v14, 0xbfb8aa3b, v6
	v_mul_f32_e32 v15, 0xbfb8aa3b, v7
	v_exp_f32_e32 v14, v14
	v_exp_f32_e32 v15, v15
	v_add_f32_e32 v14, 1.0, v14
	v_add_f32_e32 v15, 1.0, v15
	v_rcp_f32_e32 v14, v14
	v_rcp_f32_e32 v15, v15
	s_nop 0
	v_pk_mul_f32 v[6:7], v[6:7], v[14:15]
	s_nop 0
	v_pk_mul_f32 v[6:7], v[2:3], v[6:7]
	v_pk_fma_f32 v[2:3], v[8:9], v[160:161], v[84:85] op_sel_hi:[1,0,1]
	s_nop 0
	v_mul_f32_e32 v8, 0xbfb8aa3b, v2
	v_mul_f32_e32 v9, 0xbfb8aa3b, v3
	v_exp_f32_e32 v8, v8
	v_exp_f32_e32 v9, v9
	v_add_f32_e32 v8, 1.0, v8
	v_add_f32_e32 v9, 1.0, v9
	v_rcp_f32_e32 v8, v8
	v_rcp_f32_e32 v9, v9
	s_nop 0
	v_pk_mul_f32 v[2:3], v[2:3], v[8:9]
	s_nop 0
	v_pk_mul_f32 v[8:9], v[4:5], v[2:3]
	v_cvt_pk_bf16_f32 v4, v6, v7
	v_lshrrev_b32_e32 v6, 8, v175
	v_mad_i32_i24 v6, v6, 44, v161
	v_ashrrev_i32_e32 v7, 31, v6
	v_cvt_pk_bf16_f32 v5, v8, v9
	v_lshlrev_b64 v[6:7], 15, v[6:7]
	v_lshlrev_b32_e32 v8, 7, v175
	v_lshl_add_u64 v[6:7], s[12:13], 0, v[6:7]
	v_and_b32_e32 v8, 0x7f80, v8
	v_mov_b32_e32 v9, v0
	v_lshl_add_u64 v[6:7], v[6:7], 0, v[8:9]
	v_cvt_pk_bf16_f32 v2, v10, v11
	v_cvt_pk_bf16_f32 v3, v12, v13
	v_lshl_add_u64 v[6:7], v[6:7], 0, v[130:131]
	s_mov_b64 s[12:13], s[6:7]
	global_store_dwordx4 v[6:7], v[2:5], off nt
	s_cbranch_vccnz .LBB0_875
